# adds: hyena loops alternate wave halves via barriers + fragment LDS reads issued 3 fragments ahead; attention/pool staging loads issued up front
# speedup vs baseline: 1.0243x; 1.0137x over previous
.LBB0_373:
	s_and_b64 vcc, exec, s[4:5]
	s_cbranch_vccz .LBB0_428
	s_add_i32 s0, s28, 0xfffffd00
	s_lshl_b32 s4, s0, 6
	s_min_u32 s1, s4, 0x8000
	s_and_b32 s2, s1, 0xf000
	v_mov_b32_e32 v6, v167
	v_mov_b32_e32 v1, v161
	s_cmpk_lt_u32 s0, 0x200
	s_load_dwordx4 s[8:11], s[16:17], 0xd0
	s_cselect_b32 s1, s83, 0x4000
	s_sub_i32 s6, s4, s2
	v_and_b32_e32 v32, 31, v6
	s_add_i32 s6, s6, -8
	v_lshlrev_b32_e32 v2, 3, v32
	v_ashrrev_i32_e32 v8, 5, v6
	v_mov_b32_e32 v0, v1
	v_add_u32_e32 v7, s6, v8
	v_lshlrev_b32_e32 v160, 1, v2
	v_mov_b64_e32 v[4:5], v[2:3]
	v_cmp_lt_i32_e32 vcc, -1, v7
	v_cmp_gt_i32_e64 s[4:5], s1, v7
	v_mov_b64_e32 v[2:3], v[0:1]
	s_and_b64 s[12:13], vcc, s[4:5]
	v_mov_b32_e32 v3, v1
	v_mov_b32_e32 v4, v1
	v_mov_b32_e32 v5, v1
	s_waitcnt lgkmcnt(0)
	s_add_u32 s98, s10, 0xde00000
	s_addc_u32 s99, s11, 0
	v_mov_b32_e32 v236, v6
	v_ashrrev_i32_e32 v236, 5, v236
	v_add_u32_e32 v236, s6, v236
	v_mov_b32_e32 v184, v161
	v_mov_b32_e32 v185, v161
	v_mov_b32_e32 v186, v161
	v_mov_b32_e32 v187, v161
	v_cmp_lt_i32_e32 vcc, -1, v236
	v_cmp_gt_i32_e64 s[4:5], s1, v236
	s_nop 1
	s_and_b64 s[12:13], vcc, s[4:5]
	s_and_saveexec_b64 s[4:5], s[12:13]
	v_add_u32_e32 v236, s2, v236
	v_mov_b64_e32 v[238:239], s[98:99]
	v_mad_u64_u32 v[238:239], s[12:13], v236, s79, v[238:239]
	v_lshl_add_u64 v[238:239], v[238:239], 0, v[160:161]
	global_load_dwordx4 v[184:187], v[238:239], off offset:1536
	s_or_b64 exec, exec, s[4:5]
	v_add_u32_e32 v236, 512, v6
	v_ashrrev_i32_e32 v236, 5, v236
	v_add_u32_e32 v236, s6, v236
	v_mov_b32_e32 v188, v161
	v_mov_b32_e32 v189, v161
	v_mov_b32_e32 v190, v161
	v_mov_b32_e32 v191, v161
	v_cmp_lt_i32_e32 vcc, -1, v236
	v_cmp_gt_i32_e64 s[4:5], s1, v236
	s_nop 1
	s_and_b64 s[12:13], vcc, s[4:5]
	s_and_saveexec_b64 s[4:5], s[12:13]
	v_add_u32_e32 v236, s2, v236
	v_mov_b64_e32 v[238:239], s[98:99]
	v_mad_u64_u32 v[238:239], s[12:13], v236, s79, v[238:239]
	v_lshl_add_u64 v[238:239], v[238:239], 0, v[160:161]
	global_load_dwordx4 v[188:191], v[238:239], off offset:1536
	s_or_b64 exec, exec, s[4:5]
	v_add_u32_e32 v236, 1024, v6
	v_ashrrev_i32_e32 v236, 5, v236
	v_add_u32_e32 v236, s6, v236
	v_mov_b32_e32 v192, v161
	v_mov_b32_e32 v193, v161
	v_mov_b32_e32 v194, v161
	v_mov_b32_e32 v195, v161
	v_cmp_lt_i32_e32 vcc, -1, v236
	v_cmp_gt_i32_e64 s[4:5], s1, v236
	s_nop 1
	s_and_b64 s[12:13], vcc, s[4:5]
	s_and_saveexec_b64 s[4:5], s[12:13]
	v_add_u32_e32 v236, s2, v236
	v_mov_b64_e32 v[238:239], s[98:99]
	v_mad_u64_u32 v[238:239], s[12:13], v236, s79, v[238:239]
	v_lshl_add_u64 v[238:239], v[238:239], 0, v[160:161]
	global_load_dwordx4 v[192:195], v[238:239], off offset:1536
	s_or_b64 exec, exec, s[4:5]
	v_add_u32_e32 v236, 1536, v6
	v_ashrrev_i32_e32 v236, 5, v236
	v_add_u32_e32 v236, s6, v236
	v_mov_b32_e32 v196, v161
	v_mov_b32_e32 v197, v161
	v_mov_b32_e32 v198, v161
	v_mov_b32_e32 v199, v161
	v_cmp_lt_i32_e32 vcc, -1, v236
	v_cmp_gt_i32_e64 s[4:5], s1, v236
	s_nop 1
	s_and_b64 s[12:13], vcc, s[4:5]
	s_and_saveexec_b64 s[4:5], s[12:13]
	v_add_u32_e32 v236, s2, v236
	v_mov_b64_e32 v[238:239], s[98:99]
	v_mad_u64_u32 v[238:239], s[12:13], v236, s79, v[238:239]
	v_lshl_add_u64 v[238:239], v[238:239], 0, v[160:161]
	global_load_dwordx4 v[196:199], v[238:239], off offset:1536
	s_or_b64 exec, exec, s[4:5]
	v_add_u32_e32 v236, 2048, v6
	v_ashrrev_i32_e32 v236, 5, v236
	v_add_u32_e32 v236, s6, v236
	v_mov_b32_e32 v200, v161
	v_mov_b32_e32 v201, v161
	v_mov_b32_e32 v202, v161
	v_mov_b32_e32 v203, v161
	v_cmp_lt_i32_e32 vcc, -1, v236
	v_cmp_gt_i32_e64 s[4:5], s1, v236
	s_nop 1
	s_and_b64 s[12:13], vcc, s[4:5]
	s_and_saveexec_b64 s[4:5], s[12:13]
	v_add_u32_e32 v236, s2, v236
	v_mov_b64_e32 v[238:239], s[98:99]
	v_mad_u64_u32 v[238:239], s[12:13], v236, s79, v[238:239]
	v_lshl_add_u64 v[238:239], v[238:239], 0, v[160:161]
	global_load_dwordx4 v[200:203], v[238:239], off offset:1536
	s_or_b64 exec, exec, s[4:5]
	v_cmp_lt_i32_e32 vcc, -1, v7
	v_cmp_gt_i32_e64 s[4:5], s1, v7
	s_nop 1
	s_and_b64 s[12:13], vcc, s[4:5]
	s_and_saveexec_b64 s[4:5], s[12:13]
	s_cbranch_execz .LBB0_376
	v_add_u32_e32 v4, s2, v7
	s_waitcnt lgkmcnt(0)
	v_mov_b64_e32 v[2:3], s[10:11]
	v_mad_u64_u32 v[2:3], s[12:13], v4, s79, v[2:3]
	v_lshl_add_u64 v[2:3], v[2:3], 0, v[160:161]
	v_add_co_u32_e32 v2, vcc, 0xde00000, v2
	s_nop 1
	v_addc_co_u32_e32 v3, vcc, 0, v3, vcc
	s_waitcnt vmcnt(4)
	v_mov_b64_e32 v[2:3], v[184:185]
	v_mov_b64_e32 v[4:5], v[186:187]
.LBB0_376:
	s_or_b64 exec, exec, s[4:5]
	v_lshl_add_u32 v7, v32, 4, 0
	v_lshl_add_u32 v8, v8, 9, v7
	s_waitcnt vmcnt(4)
	ds_write_b128 v8, v[2:5]
	v_add_u32_e32 v2, 0x200, v6
	v_ashrrev_i32_e32 v8, 5, v2
	v_add_u32_e32 v9, s6, v8
	v_mov_b64_e32 v[4:5], v[2:3]
	v_cmp_lt_i32_e32 vcc, -1, v9
	v_cmp_gt_i32_e64 s[4:5], s1, v9
	v_mov_b64_e32 v[2:3], v[0:1]
	s_and_b64 s[12:13], vcc, s[4:5]
	v_mov_b32_e32 v3, v1
	v_mov_b32_e32 v4, v1
	v_mov_b32_e32 v5, v1
	s_and_saveexec_b64 s[4:5], s[12:13]
	s_cbranch_execz .LBB0_378
	v_add_u32_e32 v4, s2, v9
	s_waitcnt lgkmcnt(0)
	v_mov_b64_e32 v[2:3], s[10:11]
	v_mad_u64_u32 v[2:3], s[12:13], v4, s79, v[2:3]
	v_lshl_add_u64 v[2:3], v[2:3], 0, v[160:161]
	v_add_co_u32_e32 v2, vcc, 0xde00000, v2
	s_nop 1
	v_addc_co_u32_e32 v3, vcc, 0, v3, vcc
	s_waitcnt vmcnt(0)
	v_mov_b64_e32 v[2:3], v[188:189]
	v_mov_b64_e32 v[4:5], v[190:191]
.LBB0_378:
	s_or_b64 exec, exec, s[4:5]
	v_lshl_add_u32 v8, v8, 9, v7
	s_waitcnt vmcnt(0)
	ds_write_b128 v8, v[2:5]
	v_add_u32_e32 v2, 0x400, v6
	v_ashrrev_i32_e32 v8, 5, v2
	v_add_u32_e32 v9, s6, v8
	v_mov_b64_e32 v[4:5], v[2:3]
	v_cmp_lt_i32_e32 vcc, -1, v9
	v_cmp_gt_i32_e64 s[4:5], s1, v9
	v_mov_b64_e32 v[2:3], v[0:1]
	s_and_b64 s[12:13], vcc, s[4:5]
	v_mov_b32_e32 v3, v1
	v_mov_b32_e32 v4, v1
	v_mov_b32_e32 v5, v1
	s_and_saveexec_b64 s[4:5], s[12:13]
	s_cbranch_execz .LBB0_380
	v_add_u32_e32 v4, s2, v9
	s_waitcnt lgkmcnt(0)
	v_mov_b64_e32 v[2:3], s[10:11]
	v_mad_u64_u32 v[2:3], s[12:13], v4, s79, v[2:3]
	v_lshl_add_u64 v[2:3], v[2:3], 0, v[160:161]
	v_add_co_u32_e32 v2, vcc, 0xde00000, v2
	s_nop 1
	v_addc_co_u32_e32 v3, vcc, 0, v3, vcc
	s_waitcnt vmcnt(0)
	v_mov_b64_e32 v[2:3], v[192:193]
	v_mov_b64_e32 v[4:5], v[194:195]
.LBB0_380:
	s_or_b64 exec, exec, s[4:5]
	v_lshl_add_u32 v8, v8, 9, v7
	s_waitcnt vmcnt(0)
	ds_write_b128 v8, v[2:5]
	v_add_u32_e32 v2, 0x600, v6
	v_ashrrev_i32_e32 v8, 5, v2
	v_add_u32_e32 v9, s6, v8
	v_mov_b64_e32 v[4:5], v[2:3]
	v_cmp_lt_i32_e32 vcc, -1, v9
	v_cmp_gt_i32_e64 s[4:5], s1, v9
	v_mov_b64_e32 v[2:3], v[0:1]
	s_and_b64 s[12:13], vcc, s[4:5]
	v_mov_b32_e32 v3, v1
	v_mov_b32_e32 v4, v1
	v_mov_b32_e32 v5, v1
	s_and_saveexec_b64 s[4:5], s[12:13]
	s_cbranch_execz .LBB0_382
	v_add_u32_e32 v4, s2, v9
	s_waitcnt lgkmcnt(0)
	v_mov_b64_e32 v[2:3], s[10:11]
	v_mad_u64_u32 v[2:3], s[12:13], v4, s79, v[2:3]
	v_lshl_add_u64 v[2:3], v[2:3], 0, v[160:161]
	v_add_co_u32_e32 v2, vcc, 0xde00000, v2
	s_nop 1
	v_addc_co_u32_e32 v3, vcc, 0, v3, vcc
	s_waitcnt vmcnt(0)
	v_mov_b64_e32 v[2:3], v[196:197]
	v_mov_b64_e32 v[4:5], v[198:199]
.LBB0_382:
	s_or_b64 exec, exec, s[4:5]
	v_lshl_add_u32 v8, v8, 9, v7
	s_waitcnt vmcnt(0)
	ds_write_b128 v8, v[2:5]
	v_add_u32_e32 v2, 0x800, v6
	v_ashrrev_i32_e32 v4, 5, v2
	v_add_u32_e32 v5, s6, v4
	v_cmp_lt_i32_e32 vcc, -1, v5
	v_cmp_gt_i32_e64 s[4:5], s1, v5
	s_and_b64 s[6:7], vcc, s[4:5]
	v_mov_b32_e32 v2, v1
	v_mov_b32_e32 v3, v1
	s_and_saveexec_b64 s[4:5], s[6:7]
	s_cbranch_execz .LBB0_384
	v_add_u32_e32 v2, s2, v5
	s_waitcnt lgkmcnt(0)
	v_mov_b64_e32 v[0:1], s[10:11]
	v_mad_u64_u32 v[0:1], s[6:7], v2, s79, v[0:1]
	v_lshl_add_u64 v[0:1], v[0:1], 0, v[160:161]
	v_add_co_u32_e32 v0, vcc, 0xde00000, v0
	s_nop 1
	v_addc_co_u32_e32 v1, vcc, 0, v1, vcc
	s_waitcnt vmcnt(0)
	v_mov_b64_e32 v[0:1], v[200:201]
	v_mov_b64_e32 v[2:3], v[202:203]

.LBB0_394:
	v_mov_b32_e32 v15, v167
	v_mov_b32_e32 v1, v161
	s_load_dwordx4 s[8:11], s[16:17], 0xd0
	v_and_b32_e32 v14, 7, v15
	v_ashrrev_i32_e32 v28, 3, v15
	v_lshlrev_b32_e32 v2, 3, v14
	v_mov_b32_e32 v0, v1
	s_waitcnt lgkmcnt(0)
	s_add_u32 s10, s10, 0xde00000
	s_addc_u32 s11, s11, 0
	s_lshl_b32 s0, s28, 6
	s_and_b32 s37, s0, 0xffffff80
	s_min_i32 s0, s37, 0x8000
	s_and_b32 s21, s28, 1
	s_and_b32 s20, s0, 0xfffff000
	s_cmp_lt_i32 s37, 0x8000
	s_cselect_b32 s0, s83, 0x4000
	s_sub_i32 s2, s37, s20
	s_add_i32 s1, s2, 0xffffff80
	v_add_u32_e32 v3, s1, v28
	v_cmp_lt_i32_e32 vcc, -1, v3
	v_cmp_gt_i32_e64 s[4:5], s0, v3
	v_mov_b64_e32 v[12:13], v[2:3]
	s_lshl_b32 s42, s21, 6
	s_and_b64 s[6:7], vcc, s[4:5]
	v_lshlrev_b32_e32 v160, 1, v2
	v_mov_b64_e32 v[10:11], v[0:1]
	v_mov_b32_e32 v12, v1
	v_mov_b32_e32 v13, v1
	s_lshl_b32 s40, s21, 7
	v_add_u32_e32 v236, s1, v28
	v_mov_b32_e32 v184, v161
	v_mov_b32_e32 v185, v161
	v_mov_b32_e32 v186, v161
	v_mov_b32_e32 v187, v161
	v_cmp_lt_i32_e32 vcc, -1, v236
	v_cmp_gt_i32_e64 s[4:5], s0, v236
	s_nop 1
	s_and_b64 s[6:7], vcc, s[4:5]
	s_and_saveexec_b64 s[4:5], s[6:7]
	v_add_u32_e32 v236, s20, v236
	v_mov_b64_e32 v[238:239], s[10:11]
	v_mad_i64_i32 v[238:239], s[6:7], v236, s79, v[238:239]
	v_lshl_add_u64 v[238:239], v[238:239], 0, s[40:41]
	v_lshl_add_u64 v[238:239], v[238:239], 0, v[160:161]
	global_load_dwordx4 v[184:187], v[238:239], off offset:1024
	s_or_b64 exec, exec, s[4:5]
	v_add_u32_e32 v236, s1, v28
	v_add_u32_e32 v236, 64, v236
	v_mov_b32_e32 v188, v161
	v_mov_b32_e32 v189, v161
	v_mov_b32_e32 v190, v161
	v_mov_b32_e32 v191, v161
	v_cmp_lt_i32_e32 vcc, -1, v236
	v_cmp_gt_i32_e64 s[4:5], s0, v236
	s_nop 1
	s_and_b64 s[6:7], vcc, s[4:5]
	s_and_saveexec_b64 s[4:5], s[6:7]
	v_add_u32_e32 v236, s20, v236
	v_mov_b64_e32 v[238:239], s[10:11]
	v_mad_i64_i32 v[238:239], s[6:7], v236, s79, v[238:239]
	v_lshl_add_u64 v[238:239], v[238:239], 0, s[40:41]
	v_lshl_add_u64 v[238:239], v[238:239], 0, v[160:161]
	global_load_dwordx4 v[188:191], v[238:239], off offset:1024
	s_or_b64 exec, exec, s[4:5]
	v_add_u32_e32 v236, s1, v28
	v_add_u32_e32 v236, 128, v236
	v_mov_b32_e32 v192, v161
	v_mov_b32_e32 v193, v161
	v_mov_b32_e32 v194, v161
	v_mov_b32_e32 v195, v161
	v_cmp_lt_i32_e32 vcc, -1, v236
	v_cmp_gt_i32_e64 s[4:5], s0, v236
	s_nop 1
	s_and_b64 s[6:7], vcc, s[4:5]
	s_and_saveexec_b64 s[4:5], s[6:7]
	v_add_u32_e32 v236, s20, v236
	v_mov_b64_e32 v[238:239], s[10:11]
	v_mad_i64_i32 v[238:239], s[6:7], v236, s79, v[238:239]
	v_lshl_add_u64 v[238:239], v[238:239], 0, s[40:41]
	v_lshl_add_u64 v[238:239], v[238:239], 0, v[160:161]
	global_load_dwordx4 v[192:195], v[238:239], off offset:1024
	s_or_b64 exec, exec, s[4:5]
	v_add_u32_e32 v236, s1, v28
	v_add_u32_e32 v236, 192, v236
	v_mov_b32_e32 v196, v161
	v_mov_b32_e32 v197, v161
	v_mov_b32_e32 v198, v161
	v_mov_b32_e32 v199, v161
	v_cmp_lt_i32_e32 vcc, -1, v236
	v_cmp_gt_i32_e64 s[4:5], s0, v236
	s_nop 1
	s_and_b64 s[6:7], vcc, s[4:5]
	s_and_saveexec_b64 s[4:5], s[6:7]
	v_add_u32_e32 v236, s20, v236
	v_mov_b64_e32 v[238:239], s[10:11]
	v_mad_i64_i32 v[238:239], s[6:7], v236, s79, v[238:239]
	v_lshl_add_u64 v[238:239], v[238:239], 0, s[40:41]
	v_lshl_add_u64 v[238:239], v[238:239], 0, v[160:161]
	global_load_dwordx4 v[196:199], v[238:239], off offset:1024
	s_or_b64 exec, exec, s[4:5]
	v_add_u32_e32 v236, s1, v28
	v_add_u32_e32 v236, 256, v236
	v_mov_b32_e32 v200, v161
	v_mov_b32_e32 v201, v161
	v_mov_b32_e32 v202, v161
	v_mov_b32_e32 v203, v161
	v_cmp_lt_i32_e32 vcc, -1, v236
	v_cmp_gt_i32_e64 s[4:5], s0, v236
	s_nop 1
	s_and_b64 s[6:7], vcc, s[4:5]
	s_and_saveexec_b64 s[4:5], s[6:7]
	v_add_u32_e32 v236, s20, v236
	v_mov_b64_e32 v[238:239], s[10:11]
	v_mad_i64_i32 v[238:239], s[6:7], v236, s79, v[238:239]
	v_lshl_add_u64 v[238:239], v[238:239], 0, s[40:41]
	v_lshl_add_u64 v[238:239], v[238:239], 0, v[160:161]
	global_load_dwordx4 v[200:203], v[238:239], off offset:1024
	s_or_b64 exec, exec, s[4:5]
	v_add_u32_e32 v236, s1, v28
	v_add_u32_e32 v236, 320, v236
	v_mov_b32_e32 v204, v161
	v_mov_b32_e32 v205, v161
	v_mov_b32_e32 v206, v161
	v_mov_b32_e32 v207, v161
	v_cmp_lt_i32_e32 vcc, -1, v236
	v_cmp_gt_i32_e64 s[4:5], s0, v236
	s_nop 1
	s_and_b64 s[6:7], vcc, s[4:5]
	s_and_saveexec_b64 s[4:5], s[6:7]
	v_add_u32_e32 v236, s20, v236
	v_mov_b64_e32 v[238:239], s[10:11]
	v_mad_i64_i32 v[238:239], s[6:7], v236, s79, v[238:239]
	v_lshl_add_u64 v[238:239], v[238:239], 0, s[40:41]
	v_lshl_add_u64 v[238:239], v[238:239], 0, v[160:161]
	global_load_dwordx4 v[204:207], v[238:239], off offset:1024
	s_or_b64 exec, exec, s[4:5]
	v_mov_b32_e32 v236, v15
	v_mul_hi_i32 v237, v236, s84
	v_lshrrev_b32_e32 v240, 31, v237
	v_ashrrev_i32_e32 v237, 6, v237
	v_add_u32_e32 v237, v237, v240
	v_mul_i32_i24_e32 v240, 0x180, v237
	v_sub_u32_e32 v236, v236, v240
	v_add_u32_e32 v236, s1, v236
	v_mov_b32_e32 v208, v161
	v_mov_b32_e32 v209, v161
	v_mov_b32_e32 v210, v161
	v_mov_b32_e32 v211, v161
	v_cmp_lt_i32_e32 vcc, -1, v236
	v_cmp_gt_i32_e64 s[4:5], s0, v236
	s_nop 1
	s_and_b64 s[6:7], vcc, s[4:5]
	s_and_saveexec_b64 s[4:5], s[6:7]
	v_add_u32_e32 v236, s20, v236
	v_mov_b64_e32 v[238:239], s[10:11]
	v_mad_i64_i32 v[238:239], s[6:7], v236, s79, v[238:239]
	v_lshlrev_b32_e32 v240, 3, v237
	v_ashrrev_i32_e32 v241, 31, v240
	v_lshl_add_u64 v[238:239], v[238:239], 0, s[40:41]
	v_lshl_add_u64 v[238:239], v[240:241], 1, v[238:239]
	global_load_dwordx4 v[208:211], v[238:239], off offset:1280
	s_or_b64 exec, exec, s[4:5]
	v_add_u32_e32 v236, 512, v15
	v_mul_hi_i32 v237, v236, s84
	v_lshrrev_b32_e32 v240, 31, v237
	v_ashrrev_i32_e32 v237, 6, v237
	v_add_u32_e32 v237, v237, v240
	v_mul_i32_i24_e32 v240, 0x180, v237
	v_sub_u32_e32 v236, v236, v240
	v_add_u32_e32 v236, s1, v236
	v_mov_b32_e32 v212, v161
	v_mov_b32_e32 v213, v161
	v_mov_b32_e32 v214, v161
	v_mov_b32_e32 v215, v161
	v_cmp_lt_i32_e32 vcc, -1, v236
	v_cmp_gt_i32_e64 s[4:5], s0, v236
	s_nop 1
	s_and_b64 s[6:7], vcc, s[4:5]
	s_and_saveexec_b64 s[4:5], s[6:7]
	v_add_u32_e32 v236, s20, v236
	v_mov_b64_e32 v[238:239], s[10:11]
	v_mad_i64_i32 v[238:239], s[6:7], v236, s79, v[238:239]
	v_lshlrev_b32_e32 v240, 3, v237
	v_ashrrev_i32_e32 v241, 31, v240
	v_lshl_add_u64 v[238:239], v[238:239], 0, s[40:41]
	v_lshl_add_u64 v[238:239], v[240:241], 1, v[238:239]
	global_load_dwordx4 v[212:215], v[238:239], off offset:1280
	s_or_b64 exec, exec, s[4:5]
	v_add_u32_e32 v236, 1024, v15
	v_mul_hi_i32 v237, v236, s84
	v_lshrrev_b32_e32 v240, 31, v237
	v_ashrrev_i32_e32 v237, 6, v237
	v_add_u32_e32 v237, v237, v240
	v_mul_i32_i24_e32 v240, 0x180, v237
	v_sub_u32_e32 v236, v236, v240
	v_add_u32_e32 v236, s1, v236
	v_mov_b32_e32 v220, v161
	v_mov_b32_e32 v221, v161
	v_mov_b32_e32 v222, v161
	v_mov_b32_e32 v223, v161
	v_cmp_lt_i32_e32 vcc, -1, v236
	v_cmp_gt_i32_e64 s[4:5], s0, v236
	s_nop 1
	s_and_b64 s[6:7], vcc, s[4:5]
	s_and_saveexec_b64 s[4:5], s[6:7]
	v_add_u32_e32 v236, s20, v236
	v_mov_b64_e32 v[238:239], s[10:11]
	v_mad_i64_i32 v[238:239], s[6:7], v236, s79, v[238:239]
	v_lshlrev_b32_e32 v240, 3, v237
	v_ashrrev_i32_e32 v241, 31, v240
	v_lshl_add_u64 v[238:239], v[238:239], 0, s[40:41]
	v_lshl_add_u64 v[238:239], v[240:241], 1, v[238:239]
	global_load_dwordx4 v[220:223], v[238:239], off offset:1280
	s_or_b64 exec, exec, s[4:5]
	v_add_u32_e32 v236, 1536, v15
	v_mul_hi_i32 v237, v236, s84
	v_lshrrev_b32_e32 v240, 31, v237
	v_ashrrev_i32_e32 v237, 6, v237
	v_add_u32_e32 v237, v237, v240
	v_mul_i32_i24_e32 v240, 0x180, v237
	v_sub_u32_e32 v236, v236, v240
	v_add_u32_e32 v236, s1, v236
	v_mov_b32_e32 v224, v161
	v_mov_b32_e32 v225, v161
	v_mov_b32_e32 v226, v161
	v_mov_b32_e32 v227, v161
	v_cmp_lt_i32_e32 vcc, -1, v236
	v_cmp_gt_i32_e64 s[4:5], s0, v236
	s_nop 1
	s_and_b64 s[6:7], vcc, s[4:5]
	s_and_saveexec_b64 s[4:5], s[6:7]
	v_add_u32_e32 v236, s20, v236
	v_mov_b64_e32 v[238:239], s[10:11]
	v_mad_i64_i32 v[238:239], s[6:7], v236, s79, v[238:239]
	v_lshlrev_b32_e32 v240, 3, v237
	v_ashrrev_i32_e32 v241, 31, v240
	v_lshl_add_u64 v[238:239], v[238:239], 0, s[40:41]
	v_lshl_add_u64 v[238:239], v[240:241], 1, v[238:239]
	global_load_dwordx4 v[224:227], v[238:239], off offset:1280
	s_or_b64 exec, exec, s[4:5]
	v_add_u32_e32 v236, 2048, v15
	v_mul_hi_i32 v237, v236, s84
	v_lshrrev_b32_e32 v240, 31, v237
	v_ashrrev_i32_e32 v237, 6, v237
	v_add_u32_e32 v237, v237, v240
	v_mul_i32_i24_e32 v240, 0x180, v237
	v_sub_u32_e32 v236, v236, v240
	v_add_u32_e32 v236, s1, v236
	v_mov_b32_e32 v228, v161
	v_mov_b32_e32 v229, v161
	v_mov_b32_e32 v230, v161
	v_mov_b32_e32 v231, v161
	v_cmp_lt_i32_e32 vcc, -1, v236
	v_cmp_gt_i32_e64 s[4:5], s0, v236
	s_nop 1
	s_and_b64 s[6:7], vcc, s[4:5]
	s_and_saveexec_b64 s[4:5], s[6:7]
	v_add_u32_e32 v236, s20, v236
	v_mov_b64_e32 v[238:239], s[10:11]
	v_mad_i64_i32 v[238:239], s[6:7], v236, s79, v[238:239]
	v_lshlrev_b32_e32 v240, 3, v237
	v_ashrrev_i32_e32 v241, 31, v240
	v_lshl_add_u64 v[238:239], v[238:239], 0, s[40:41]
	v_lshl_add_u64 v[238:239], v[240:241], 1, v[238:239]
	global_load_dwordx4 v[228:231], v[238:239], off offset:1280
	s_or_b64 exec, exec, s[4:5]
	v_add_u32_e32 v236, 2560, v15
	v_mul_hi_i32 v237, v236, s84
	v_lshrrev_b32_e32 v240, 31, v237
	v_ashrrev_i32_e32 v237, 6, v237
	v_add_u32_e32 v237, v237, v240
	v_mul_i32_i24_e32 v240, 0x180, v237
	v_sub_u32_e32 v236, v236, v240
	v_add_u32_e32 v236, s1, v236
	v_mov_b32_e32 v232, v161
	v_mov_b32_e32 v233, v161
	v_mov_b32_e32 v234, v161
	v_mov_b32_e32 v235, v161
	v_cmp_lt_i32_e32 vcc, -1, v236
	v_cmp_gt_i32_e64 s[4:5], s0, v236
	s_nop 1
	s_and_b64 s[6:7], vcc, s[4:5]
	s_and_saveexec_b64 s[4:5], s[6:7]
	v_add_u32_e32 v236, s20, v236
	v_mov_b64_e32 v[238:239], s[10:11]
	v_mad_i64_i32 v[238:239], s[6:7], v236, s79, v[238:239]
	v_lshlrev_b32_e32 v240, 3, v237
	v_ashrrev_i32_e32 v241, 31, v240
	v_lshl_add_u64 v[238:239], v[238:239], 0, s[40:41]
	v_lshl_add_u64 v[238:239], v[240:241], 1, v[238:239]
	global_load_dwordx4 v[232:235], v[238:239], off offset:1280
	s_or_b64 exec, exec, s[4:5]
	v_cmp_lt_i32_e32 vcc, -1, v3
	v_cmp_gt_i32_e64 s[4:5], s0, v3
	s_nop 1
	s_and_b64 s[6:7], vcc, s[4:5]
	s_and_saveexec_b64 s[4:5], s[6:7]
	s_cbranch_execz .LBB0_396
	v_add_u32_e32 v3, s20, v3
	v_mov_b64_e32 v[4:5], s[10:11]
	v_mad_i64_i32 v[4:5], s[6:7], v3, s79, v[4:5]
	s_lshl_b32 s40, s42, 1
	v_lshl_add_u64 v[4:5], v[4:5], 0, s[40:41]
	v_lshl_add_u64 v[4:5], v[4:5], 0, v[160:161]
	s_waitcnt vmcnt(11)
	v_mov_b64_e32 v[10:11], v[184:185]
	v_mov_b64_e32 v[12:13], v[186:187]
.LBB0_396:
	s_or_b64 exec, exec, s[4:5]
	s_load_dwordx4 s[12:15], s[16:17], 0x20
	v_lshlrev_b32_e32 v2, 2, v2
	s_waitcnt vmcnt(11)
	v_lshlrev_b32_e32 v22, 16, v10
	v_and_b32_e32 v23, 0xffff0000, v10
	v_lshlrev_b32_e32 v20, 16, v11
	s_waitcnt lgkmcnt(0)
	s_add_u32 s4, s14, s26
	s_addc_u32 s5, s15, s27
	global_load_dwordx4 v[6:9], v2, s[4:5]
	s_nop 0
	global_load_dwordx4 v[2:5], v2, s[4:5] offset:16
	v_and_b32_e32 v21, 0xffff0000, v11
	v_pk_mul_f32 v[26:27], v[22:23], v[22:23]
	v_pk_mul_f32 v[30:31], v[20:21], v[20:21]
	v_add_f32_e32 v27, v26, v27
	v_lshlrev_b32_e32 v18, 16, v12
	v_and_b32_e32 v19, 0xffff0000, v12
	v_add_f32_e32 v27, v30, v27
	v_and_b32_e32 v24, 64, v217
	v_lshlrev_b32_e32 v16, 16, v13
	v_and_b32_e32 v17, 0xffff0000, v13
	v_pk_mul_f32 v[12:13], v[18:19], v[18:19]
	v_add_f32_e32 v27, v31, v27
	v_xor_b32_e32 v29, 1, v217
	v_add_u32_e32 v24, 64, v24
	v_add_f32_e32 v12, v12, v27
	v_pk_mul_f32 v[10:11], v[16:17], v[16:17]
	v_cmp_lt_i32_e32 vcc, v29, v24
	v_add_f32_e32 v12, v13, v12
	v_add_f32_e32 v10, v10, v12
	v_cndmask_b32_e32 v29, v217, v29, vcc
	v_lshlrev_b32_e32 v26, 2, v29
	v_add_f32_e32 v29, v11, v10
	ds_bpermute_b32 v30, v26, v29
	v_xor_b32_e32 v32, 2, v217
	v_cmp_lt_i32_e32 vcc, v32, v24
	v_xor_b32_e32 v34, 4, v217
	v_lshl_add_u32 v14, v14, 4, 0
	v_add_u32_e32 v25, 0x200, v15
	s_waitcnt vmcnt(0)
	v_mov_b64_e32 v[12:13], v[2:3]
	v_mov_b64_e32 v[10:11], v[0:1]
	v_cndmask_b32_e32 v11, v217, v32, vcc
	v_lshlrev_b32_e32 v27, 2, v11
	s_waitcnt lgkmcnt(0)
	v_add_f32_e32 v11, v29, v30
	ds_bpermute_b32 v12, v27, v11
	v_cmp_lt_i32_e32 vcc, v34, v24
	v_mad_u64_u32 v[32:33], s[4:5], v28, s80, v[14:15]
	s_nop 0
	v_cndmask_b32_e32 v13, v217, v34, vcc
	v_lshlrev_b32_e32 v28, 2, v13
	s_waitcnt lgkmcnt(0)
	v_add_f32_e32 v13, v11, v12
	ds_bpermute_b32 v31, v28, v13
	v_ashrrev_i32_e32 v29, 3, v25
	v_add_u32_e32 v30, s1, v29
	v_cmp_lt_i32_e64 s[4:5], -1, v30
	v_cmp_gt_i32_e64 s[6:7], s0, v30
	s_waitcnt lgkmcnt(0)
	v_add_f32_e32 v13, v13, v31
	v_fmamk_f32 v13, v13, 0x3c800000, v166
	v_mul_f32_e32 v31, 0x4b800000, v13
	v_cmp_gt_f32_e32 vcc, s78, v13
	v_mov_b32_e32 v11, v1
	v_mov_b32_e32 v12, v1
	v_cndmask_b32_e32 v13, v13, v31, vcc
	v_rsq_f32_e32 v13, v13
	s_and_b64 s[6:7], s[4:5], s[6:7]
	v_mul_f32_e32 v31, 0x45800000, v13
	v_cndmask_b32_e32 v34, v13, v31, vcc
	v_pk_mul_f32 v[36:37], v[6:7], v[34:35] op_sel_hi:[1,0]
	v_pk_mul_f32 v[38:39], v[8:9], v[34:35] op_sel_hi:[1,0]
	v_pk_mul_f32 v[40:41], v[2:3], v[34:35] op_sel_hi:[1,0]
	v_pk_mul_f32 v[34:35], v[4:5], v[34:35] op_sel_hi:[1,0]
	v_pk_mul_f32 v[22:23], v[36:37], v[22:23]
	v_pk_mul_f32 v[20:21], v[38:39], v[20:21]
	v_pk_mul_f32 v[18:19], v[40:41], v[18:19]
	v_pk_mul_f32 v[34:35], v[34:35], v[16:17]
	v_cvt_pk_bf16_f32 v16, v22, v23
	v_cvt_pk_bf16_f32 v17, v20, v21
	v_cvt_pk_bf16_f32 v18, v18, v19
	v_cvt_pk_bf16_f32 v19, v34, v35
	v_mov_b32_e32 v13, v1
	ds_write_b128 v32, v[16:19]
	s_and_saveexec_b64 s[4:5], s[6:7]
	s_cbranch_execz .LBB0_398
	v_add_u32_e32 v12, s20, v30
	v_mov_b64_e32 v[10:11], s[10:11]
	v_mad_i64_i32 v[10:11], s[6:7], v12, s79, v[10:11]
	s_lshl_b32 s40, s42, 1
	v_lshl_add_u64 v[10:11], v[10:11], 0, s[40:41]
	v_lshl_add_u64 v[10:11], v[10:11], 0, v[160:161]
	s_waitcnt vmcnt(0)
	v_mov_b64_e32 v[10:11], v[188:189]
	v_mov_b64_e32 v[12:13], v[190:191]
.LBB0_398:
	s_or_b64 exec, exec, s[4:5]
	s_waitcnt vmcnt(0)
	v_lshlrev_b32_e32 v32, 16, v10
	v_and_b32_e32 v33, 0xffff0000, v10
	v_lshlrev_b32_e32 v22, 16, v11
	v_and_b32_e32 v23, 0xffff0000, v11
	v_pk_mul_f32 v[10:11], v[32:33], v[32:33]
	v_pk_mul_f32 v[30:31], v[22:23], v[22:23]
	v_add_f32_e32 v10, v10, v11
	v_lshlrev_b32_e32 v20, 16, v12
	v_and_b32_e32 v21, 0xffff0000, v12
	v_add_f32_e32 v10, v30, v10
	v_lshlrev_b32_e32 v16, 16, v13
	v_and_b32_e32 v17, 0xffff0000, v13
	v_pk_mul_f32 v[12:13], v[20:21], v[20:21]
	v_add_f32_e32 v10, v31, v10
	v_add_f32_e32 v10, v12, v10
	v_pk_mul_f32 v[18:19], v[16:17], v[16:17]
	v_add_f32_e32 v10, v13, v10
	v_add_f32_e32 v10, v18, v10
	v_add_f32_e32 v10, v19, v10
	ds_bpermute_b32 v11, v26, v10
	s_waitcnt lgkmcnt(0)
	v_add_f32_e32 v10, v10, v11
	ds_bpermute_b32 v11, v27, v10
	s_waitcnt lgkmcnt(0)
	v_add_f32_e32 v10, v10, v11
	ds_bpermute_b32 v11, v28, v10
	s_waitcnt lgkmcnt(0)
	v_add_f32_e32 v10, v10, v11
	v_fmamk_f32 v10, v10, 0x3c800000, v166
	v_mul_f32_e32 v11, 0x4b800000, v10
	v_cmp_gt_f32_e32 vcc, s78, v10
	s_nop 1
	v_cndmask_b32_e32 v10, v10, v11, vcc
	v_rsq_f32_e32 v10, v10
	s_nop 0
	v_mul_f32_e32 v11, 0x45800000, v10
	v_cndmask_b32_e32 v10, v10, v11, vcc
	v_pk_mul_f32 v[12:13], v[6:7], v[10:11] op_sel_hi:[1,0]
	v_pk_mul_f32 v[18:19], v[8:9], v[10:11] op_sel_hi:[1,0]
	v_pk_mul_f32 v[30:31], v[2:3], v[10:11] op_sel_hi:[1,0]
	v_pk_mul_f32 v[10:11], v[4:5], v[10:11] op_sel_hi:[1,0]
	v_pk_mul_f32 v[12:13], v[12:13], v[32:33]
	v_pk_mul_f32 v[18:19], v[18:19], v[22:23]
	v_pk_mul_f32 v[20:21], v[30:31], v[20:21]
	v_pk_mul_f32 v[16:17], v[10:11], v[16:17]
	v_cvt_pk_bf16_f32 v10, v12, v13
	v_cvt_pk_bf16_f32 v11, v18, v19
	v_cvt_pk_bf16_f32 v12, v20, v21
	v_cvt_pk_bf16_f32 v13, v16, v17
	v_mad_u64_u32 v[16:17], s[4:5], v29, s80, v[14:15]
	ds_write_b128 v16, v[10:13]
	v_add_u32_e32 v16, 0x400, v15
	v_ashrrev_i32_e32 v17, 3, v16
	v_add_u32_e32 v18, s1, v17
	v_cmp_lt_i32_e32 vcc, -1, v18
	v_cmp_gt_i32_e64 s[4:5], s0, v18
	v_mov_b64_e32 v[12:13], v[2:3]
	s_and_b64 s[6:7], vcc, s[4:5]
	v_mov_b64_e32 v[10:11], v[0:1]
	v_mov_b32_e32 v12, v1
	v_mov_b32_e32 v13, v1
	s_and_saveexec_b64 s[4:5], s[6:7]
	s_cbranch_execz .LBB0_400
	v_add_u32_e32 v12, s20, v18
	v_mov_b64_e32 v[10:11], s[10:11]
	v_mad_i64_i32 v[10:11], s[6:7], v12, s79, v[10:11]
	s_lshl_b32 s40, s42, 1
	v_lshl_add_u64 v[10:11], v[10:11], 0, s[40:41]
	v_lshl_add_u64 v[10:11], v[10:11], 0, v[160:161]
	s_waitcnt vmcnt(0)
	v_mov_b64_e32 v[10:11], v[192:193]
	v_mov_b64_e32 v[12:13], v[194:195]
.LBB0_400:
	s_or_b64 exec, exec, s[4:5]
	s_waitcnt vmcnt(0)
	v_lshlrev_b32_e32 v34, 16, v10
	v_and_b32_e32 v35, 0xffff0000, v10
	v_lshlrev_b32_e32 v30, 16, v11
	v_and_b32_e32 v31, 0xffff0000, v11
	v_pk_mul_f32 v[10:11], v[34:35], v[34:35]
	v_pk_mul_f32 v[32:33], v[30:31], v[30:31]
	v_add_f32_e32 v10, v10, v11
	v_lshlrev_b32_e32 v22, 16, v12
	v_and_b32_e32 v23, 0xffff0000, v12
	v_add_f32_e32 v10, v32, v10
	v_lshlrev_b32_e32 v18, 16, v13
	v_and_b32_e32 v19, 0xffff0000, v13
	v_pk_mul_f32 v[12:13], v[22:23], v[22:23]
	v_add_f32_e32 v10, v33, v10
	v_add_f32_e32 v10, v12, v10
	v_pk_mul_f32 v[20:21], v[18:19], v[18:19]
	v_add_f32_e32 v10, v13, v10
	v_add_f32_e32 v10, v20, v10
	v_add_f32_e32 v10, v21, v10
	ds_bpermute_b32 v11, v26, v10
	s_waitcnt lgkmcnt(0)
	v_add_f32_e32 v10, v10, v11
	ds_bpermute_b32 v11, v27, v10
	s_waitcnt lgkmcnt(0)
	v_add_f32_e32 v10, v10, v11
	ds_bpermute_b32 v11, v28, v10
	s_waitcnt lgkmcnt(0)
	v_add_f32_e32 v10, v10, v11
	v_fmamk_f32 v10, v10, 0x3c800000, v166
	v_mul_f32_e32 v11, 0x4b800000, v10
	v_cmp_gt_f32_e32 vcc, s78, v10
	s_nop 1
	v_cndmask_b32_e32 v10, v10, v11, vcc
	v_rsq_f32_e32 v10, v10
	s_nop 0
	v_mul_f32_e32 v11, 0x45800000, v10
	v_cndmask_b32_e32 v10, v10, v11, vcc
	v_pk_mul_f32 v[12:13], v[6:7], v[10:11] op_sel_hi:[1,0]
	v_pk_mul_f32 v[20:21], v[8:9], v[10:11] op_sel_hi:[1,0]
	v_pk_mul_f32 v[32:33], v[2:3], v[10:11] op_sel_hi:[1,0]
	v_pk_mul_f32 v[10:11], v[4:5], v[10:11] op_sel_hi:[1,0]
	v_pk_mul_f32 v[12:13], v[12:13], v[34:35]
	v_pk_mul_f32 v[20:21], v[20:21], v[30:31]
	v_pk_mul_f32 v[22:23], v[32:33], v[22:23]
	v_pk_mul_f32 v[18:19], v[10:11], v[18:19]
	v_cvt_pk_bf16_f32 v10, v12, v13
	v_cvt_pk_bf16_f32 v11, v20, v21
	v_cvt_pk_bf16_f32 v12, v22, v23
	v_cvt_pk_bf16_f32 v13, v18, v19
	v_mad_u64_u32 v[18:19], s[4:5], v17, s80, v[14:15]
	v_add_u32_e32 v17, 0x600, v15
	ds_write_b128 v18, v[10:13]
	v_ashrrev_i32_e32 v18, 3, v17
	v_add_u32_e32 v19, s1, v18
	v_cmp_lt_i32_e32 vcc, -1, v19
	v_cmp_gt_i32_e64 s[4:5], s0, v19
	v_mov_b64_e32 v[12:13], v[2:3]
	s_and_b64 s[6:7], vcc, s[4:5]
	v_mov_b64_e32 v[10:11], v[0:1]
	v_mov_b32_e32 v12, v1
	v_mov_b32_e32 v13, v1
	s_and_saveexec_b64 s[4:5], s[6:7]
	s_cbranch_execz .LBB0_402
	v_add_u32_e32 v12, s20, v19
	v_mov_b64_e32 v[10:11], s[10:11]
	v_mad_i64_i32 v[10:11], s[6:7], v12, s79, v[10:11]
	s_lshl_b32 s40, s42, 1
	v_lshl_add_u64 v[10:11], v[10:11], 0, s[40:41]
	v_lshl_add_u64 v[10:11], v[10:11], 0, v[160:161]
	s_waitcnt vmcnt(0)
	v_mov_b64_e32 v[10:11], v[196:197]
	v_mov_b64_e32 v[12:13], v[198:199]
.LBB0_402:
	s_or_b64 exec, exec, s[4:5]
	s_waitcnt vmcnt(0)
	v_lshlrev_b32_e32 v36, 16, v10
	v_and_b32_e32 v37, 0xffff0000, v10
	v_lshlrev_b32_e32 v32, 16, v11
	v_and_b32_e32 v33, 0xffff0000, v11
	v_pk_mul_f32 v[10:11], v[36:37], v[36:37]
	v_pk_mul_f32 v[34:35], v[32:33], v[32:33]
	v_add_f32_e32 v10, v10, v11
	v_lshlrev_b32_e32 v30, 16, v12
	v_and_b32_e32 v31, 0xffff0000, v12
	v_add_f32_e32 v10, v34, v10
	v_lshlrev_b32_e32 v20, 16, v13
	v_and_b32_e32 v21, 0xffff0000, v13
	v_pk_mul_f32 v[12:13], v[30:31], v[30:31]
	v_add_f32_e32 v10, v35, v10
	v_add_f32_e32 v10, v12, v10
	v_pk_mul_f32 v[22:23], v[20:21], v[20:21]
	v_add_f32_e32 v10, v13, v10
	v_add_f32_e32 v10, v22, v10
	v_add_f32_e32 v10, v23, v10
	ds_bpermute_b32 v11, v26, v10
	v_mad_u64_u32 v[18:19], s[4:5], v18, s80, v[14:15]
	s_waitcnt lgkmcnt(0)
	v_add_f32_e32 v10, v10, v11
	ds_bpermute_b32 v11, v27, v10
	s_waitcnt lgkmcnt(0)
	v_add_f32_e32 v10, v10, v11
	ds_bpermute_b32 v11, v28, v10
	s_waitcnt lgkmcnt(0)
	v_add_f32_e32 v10, v10, v11
	v_fmamk_f32 v10, v10, 0x3c800000, v166
	v_mul_f32_e32 v11, 0x4b800000, v10
	v_cmp_gt_f32_e32 vcc, s78, v10
	s_nop 1
	v_cndmask_b32_e32 v10, v10, v11, vcc
	v_rsq_f32_e32 v10, v10
	s_nop 0
	v_mul_f32_e32 v11, 0x45800000, v10
	v_cndmask_b32_e32 v10, v10, v11, vcc
	v_pk_mul_f32 v[12:13], v[6:7], v[10:11] op_sel_hi:[1,0]
	v_pk_mul_f32 v[22:23], v[8:9], v[10:11] op_sel_hi:[1,0]
	v_pk_mul_f32 v[34:35], v[2:3], v[10:11] op_sel_hi:[1,0]
	v_pk_mul_f32 v[10:11], v[4:5], v[10:11] op_sel_hi:[1,0]
	v_pk_mul_f32 v[12:13], v[12:13], v[36:37]
	v_pk_mul_f32 v[22:23], v[22:23], v[32:33]
	v_pk_mul_f32 v[30:31], v[34:35], v[30:31]
	v_pk_mul_f32 v[20:21], v[10:11], v[20:21]
	v_cvt_pk_bf16_f32 v10, v12, v13
	v_cvt_pk_bf16_f32 v11, v22, v23
	v_cvt_pk_bf16_f32 v12, v30, v31
	v_cvt_pk_bf16_f32 v13, v20, v21
	ds_write_b128 v18, v[10:13]
	v_add_u32_e32 v18, 0x800, v15
	v_ashrrev_i32_e32 v19, 3, v18
	v_add_u32_e32 v20, s1, v19
	v_cmp_lt_i32_e32 vcc, -1, v20
	v_cmp_gt_i32_e64 s[4:5], s0, v20
	v_mov_b64_e32 v[12:13], v[2:3]
	s_and_b64 s[6:7], vcc, s[4:5]
	v_mov_b64_e32 v[10:11], v[0:1]
	v_mov_b32_e32 v12, v1
	v_mov_b32_e32 v13, v1
	s_and_saveexec_b64 s[4:5], s[6:7]
	s_cbranch_execz .LBB0_404
	v_add_u32_e32 v12, s20, v20
	v_mov_b64_e32 v[10:11], s[10:11]
	v_mad_i64_i32 v[10:11], s[6:7], v12, s79, v[10:11]
	s_lshl_b32 s40, s42, 1
	v_lshl_add_u64 v[10:11], v[10:11], 0, s[40:41]
	v_lshl_add_u64 v[10:11], v[10:11], 0, v[160:161]
	s_waitcnt vmcnt(0)
	v_mov_b64_e32 v[10:11], v[200:201]
	v_mov_b64_e32 v[12:13], v[202:203]
.LBB0_404:
	s_or_b64 exec, exec, s[4:5]
	s_waitcnt vmcnt(0)
	v_lshlrev_b32_e32 v36, 16, v10
	v_and_b32_e32 v37, 0xffff0000, v10
	v_lshlrev_b32_e32 v32, 16, v11
	v_and_b32_e32 v33, 0xffff0000, v11
	v_pk_mul_f32 v[10:11], v[36:37], v[36:37]
	v_pk_mul_f32 v[34:35], v[32:33], v[32:33]
	v_add_f32_e32 v10, v10, v11
	v_lshlrev_b32_e32 v30, 16, v12
	v_and_b32_e32 v31, 0xffff0000, v12
	v_add_f32_e32 v10, v34, v10
	v_lshlrev_b32_e32 v20, 16, v13
	v_and_b32_e32 v21, 0xffff0000, v13
	v_pk_mul_f32 v[12:13], v[30:31], v[30:31]
	v_add_f32_e32 v10, v35, v10
	v_add_f32_e32 v10, v12, v10
	v_pk_mul_f32 v[22:23], v[20:21], v[20:21]
	v_add_f32_e32 v10, v13, v10
	v_add_f32_e32 v10, v22, v10
	v_add_f32_e32 v10, v23, v10
	ds_bpermute_b32 v11, v26, v10
	s_waitcnt lgkmcnt(0)
	v_add_f32_e32 v10, v10, v11
	ds_bpermute_b32 v11, v27, v10
	s_waitcnt lgkmcnt(0)
	v_add_f32_e32 v10, v10, v11
	ds_bpermute_b32 v11, v28, v10
	s_waitcnt lgkmcnt(0)
	v_add_f32_e32 v10, v10, v11
	v_fmamk_f32 v10, v10, 0x3c800000, v166
	v_mul_f32_e32 v11, 0x4b800000, v10
	v_cmp_gt_f32_e32 vcc, s78, v10
	s_nop 1
	v_cndmask_b32_e32 v10, v10, v11, vcc
	v_rsq_f32_e32 v10, v10
	s_nop 0
	v_mul_f32_e32 v11, 0x45800000, v10
	v_cndmask_b32_e32 v10, v10, v11, vcc
	v_pk_mul_f32 v[12:13], v[6:7], v[10:11] op_sel_hi:[1,0]
	v_pk_mul_f32 v[22:23], v[8:9], v[10:11] op_sel_hi:[1,0]
	v_pk_mul_f32 v[34:35], v[2:3], v[10:11] op_sel_hi:[1,0]
	v_pk_mul_f32 v[10:11], v[4:5], v[10:11] op_sel_hi:[1,0]
	v_pk_mul_f32 v[12:13], v[12:13], v[36:37]
	v_pk_mul_f32 v[22:23], v[22:23], v[32:33]
	v_pk_mul_f32 v[30:31], v[34:35], v[30:31]
	v_pk_mul_f32 v[20:21], v[10:11], v[20:21]
	v_cvt_pk_bf16_f32 v10, v12, v13
	v_cvt_pk_bf16_f32 v11, v22, v23
	v_cvt_pk_bf16_f32 v12, v30, v31
	v_cvt_pk_bf16_f32 v13, v20, v21
	v_mad_u64_u32 v[20:21], s[4:5], v19, s80, v[14:15]
	v_add_u32_e32 v19, 0xa00, v15
	ds_write_b128 v20, v[10:13]
	v_ashrrev_i32_e32 v20, 3, v19
	v_add_u32_e32 v21, s1, v20
	v_cmp_lt_i32_e32 vcc, -1, v21
	v_cmp_gt_i32_e64 s[4:5], s0, v21
	v_mov_b64_e32 v[12:13], v[2:3]
	s_and_b64 s[6:7], vcc, s[4:5]
	v_mov_b64_e32 v[10:11], v[0:1]
	v_mov_b32_e32 v12, v1
	v_mov_b32_e32 v13, v1
	s_and_saveexec_b64 s[4:5], s[6:7]
	s_cbranch_execz .LBB0_406
	v_add_u32_e32 v12, s20, v21
	v_mov_b64_e32 v[10:11], s[10:11]
	v_mad_i64_i32 v[10:11], s[6:7], v12, s79, v[10:11]
	s_lshl_b32 s40, s42, 1
	v_lshl_add_u64 v[10:11], v[10:11], 0, s[40:41]
	v_lshl_add_u64 v[10:11], v[10:11], 0, v[160:161]
	s_waitcnt vmcnt(0)
	v_mov_b64_e32 v[10:11], v[204:205]
	v_mov_b64_e32 v[12:13], v[206:207]
.LBB0_406:
	s_or_b64 exec, exec, s[4:5]
	s_waitcnt vmcnt(0)
	v_lshlrev_b32_e32 v38, 16, v10
	v_and_b32_e32 v39, 0xffff0000, v10
	v_lshlrev_b32_e32 v34, 16, v11
	v_and_b32_e32 v35, 0xffff0000, v11
	v_pk_mul_f32 v[10:11], v[38:39], v[38:39]
	v_pk_mul_f32 v[36:37], v[34:35], v[34:35]
	v_add_f32_e32 v10, v10, v11
	v_lshlrev_b32_e32 v32, 16, v12
	v_and_b32_e32 v33, 0xffff0000, v12
	v_add_f32_e32 v10, v36, v10
	v_lshlrev_b32_e32 v22, 16, v13
	v_and_b32_e32 v23, 0xffff0000, v13
	v_pk_mul_f32 v[12:13], v[32:33], v[32:33]
	v_add_f32_e32 v10, v37, v10
	v_add_f32_e32 v10, v12, v10
	v_pk_mul_f32 v[30:31], v[22:23], v[22:23]
	v_add_f32_e32 v10, v13, v10
	v_add_f32_e32 v10, v30, v10
	v_add_f32_e32 v10, v31, v10
	ds_bpermute_b32 v11, v26, v10
	s_waitcnt lgkmcnt(0)
	v_add_f32_e32 v10, v10, v11
	ds_bpermute_b32 v11, v27, v10
	s_waitcnt lgkmcnt(0)
	v_add_f32_e32 v10, v10, v11
	ds_bpermute_b32 v11, v28, v10
	s_waitcnt lgkmcnt(0)
	v_add_f32_e32 v10, v10, v11
	v_fmamk_f32 v10, v10, 0x3c800000, v166
	v_mul_f32_e32 v11, 0x4b800000, v10
	v_cmp_gt_f32_e32 vcc, s78, v10
	s_nop 1
	v_cndmask_b32_e32 v10, v10, v11, vcc
	v_rsq_f32_e32 v10, v10
	s_nop 0
	v_mul_f32_e32 v11, 0x45800000, v10
	v_cndmask_b32_e32 v10, v10, v11, vcc
	v_pk_mul_f32 v[2:3], v[2:3], v[10:11] op_sel_hi:[1,0]
	v_pk_mul_f32 v[6:7], v[6:7], v[10:11] op_sel_hi:[1,0]
	v_pk_mul_f32 v[8:9], v[8:9], v[10:11] op_sel_hi:[1,0]
	v_pk_mul_f32 v[12:13], v[2:3], v[32:33]
	v_pk_mul_f32 v[2:3], v[4:5], v[10:11] op_sel_hi:[1,0]
	v_pk_mul_f32 v[6:7], v[6:7], v[38:39]
	v_pk_mul_f32 v[8:9], v[8:9], v[34:35]
	v_pk_mul_f32 v[10:11], v[2:3], v[22:23]
	v_cvt_pk_bf16_f32 v2, v6, v7
	v_cvt_pk_bf16_f32 v3, v8, v9
	v_cvt_pk_bf16_f32 v4, v12, v13
	v_cvt_pk_bf16_f32 v5, v10, v11
	v_mad_u64_u32 v[6:7], s[4:5], v20, s80, v[14:15]
	ds_write_b128 v6, v[2:5]
	v_mul_hi_i32 v2, v15, s84
	v_lshrrev_b32_e32 v3, 31, v2
	v_ashrrev_i32_e32 v2, 6, v2
	v_add_u32_e32 v6, v2, v3
	v_mul_i32_i24_e32 v2, 0x180, v6
	v_sub_u32_e32 v7, v15, v2
	v_add_u32_e32 v8, s1, v7
	v_mov_b64_e32 v[4:5], v[2:3]
	v_cmp_lt_i32_e32 vcc, -1, v8
	v_cmp_gt_i32_e64 s[4:5], s0, v8
	v_mov_b64_e32 v[2:3], v[0:1]
	s_and_b64 s[6:7], vcc, s[4:5]
	v_mov_b32_e32 v3, v1
	v_mov_b32_e32 v4, v1
	v_mov_b32_e32 v5, v1
	s_and_saveexec_b64 s[4:5], s[6:7]
	s_cbranch_execz .LBB0_408
	v_add_u32_e32 v4, s20, v8
	v_mov_b64_e32 v[2:3], s[10:11]
	v_mad_i64_i32 v[2:3], s[6:7], v4, s79, v[2:3]
	s_lshl_b32 s40, s42, 1
	v_lshlrev_b32_e32 v4, 3, v6
	v_lshl_add_u64 v[2:3], v[2:3], 0, s[40:41]
	v_ashrrev_i32_e32 v5, 31, v4
	v_lshl_add_u64 v[2:3], v[4:5], 1, v[2:3]
	s_waitcnt vmcnt(0)
	v_mov_b64_e32 v[2:3], v[208:209]
	v_mov_b64_e32 v[4:5], v[210:211]
.LBB0_408:
	s_or_b64 exec, exec, s[4:5]
	v_mul_i32_i24_e32 v6, 0x1880, v6
	v_lshlrev_b32_e32 v7, 1, v7
	v_add3_u32 v6, 0, v6, v7
	s_waitcnt vmcnt(0)
	ds_write_b16 v6, v2 offset:55296
	ds_write_b16_d16_hi v6, v2 offset:56080
	ds_write_b16 v6, v3 offset:56864
	ds_write_b16_d16_hi v6, v3 offset:57648
	ds_write_b16 v6, v4 offset:58432
	ds_write_b16_d16_hi v6, v4 offset:59216
	ds_write_b16 v6, v5 offset:60000
	ds_write_b16_d16_hi v6, v5 offset:60784
	v_mul_hi_i32 v2, v25, s84
	v_lshrrev_b32_e32 v3, 31, v2
	v_ashrrev_i32_e32 v2, 6, v2
	v_add_u32_e32 v6, v2, v3
	v_mul_i32_i24_e32 v7, 0x180, v6
	v_sub_u32_e32 v2, v25, v7
	v_add_u32_e32 v8, s1, v2
	v_mov_b64_e32 v[4:5], v[2:3]
	v_cmp_lt_i32_e32 vcc, -1, v8
	v_cmp_gt_i32_e64 s[4:5], s0, v8
	v_mov_b64_e32 v[2:3], v[0:1]
	s_and_b64 s[6:7], vcc, s[4:5]
	v_mov_b32_e32 v3, v1
	v_mov_b32_e32 v4, v1
	v_mov_b32_e32 v5, v1
	s_and_saveexec_b64 s[4:5], s[6:7]
	s_cbranch_execz .LBB0_410
	v_add_u32_e32 v4, s20, v8
	v_mov_b64_e32 v[2:3], s[10:11]
	v_mad_i64_i32 v[2:3], s[6:7], v4, s79, v[2:3]
	s_lshl_b32 s40, s42, 1
	v_lshlrev_b32_e32 v4, 3, v6
	v_lshl_add_u64 v[2:3], v[2:3], 0, s[40:41]
	v_ashrrev_i32_e32 v5, 31, v4
	v_lshl_add_u64 v[2:3], v[4:5], 1, v[2:3]
	s_waitcnt vmcnt(0)
	v_mov_b64_e32 v[2:3], v[212:213]
	v_mov_b64_e32 v[4:5], v[214:215]
.LBB0_410:
	s_or_b64 exec, exec, s[4:5]
	v_sub_u32_e32 v7, v15, v7
	v_mul_i32_i24_e32 v6, 0x1880, v6
	v_lshlrev_b32_e32 v7, 1, v7
	v_add3_u32 v6, 0, v6, v7
	s_waitcnt vmcnt(0)
	ds_write_b16 v6, v2 offset:56320
	ds_write_b16_d16_hi v6, v2 offset:57104
	ds_write_b16 v6, v3 offset:57888
	ds_write_b16_d16_hi v6, v3 offset:58672
	ds_write_b16 v6, v4 offset:59456
	ds_write_b16_d16_hi v6, v4 offset:60240
	ds_write_b16 v6, v5 offset:61024
	ds_write_b16_d16_hi v6, v5 offset:61808
	v_mul_hi_i32 v2, v16, s84
	v_lshrrev_b32_e32 v3, 31, v2
	v_ashrrev_i32_e32 v2, 6, v2
	v_add_u32_e32 v6, v2, v3
	v_mul_i32_i24_e32 v7, 0x180, v6
	v_sub_u32_e32 v2, v16, v7
	v_add_u32_e32 v8, s1, v2
	v_mov_b64_e32 v[4:5], v[2:3]
	v_cmp_lt_i32_e32 vcc, -1, v8
	v_cmp_gt_i32_e64 s[4:5], s0, v8
	v_mov_b64_e32 v[2:3], v[0:1]
	s_and_b64 s[6:7], vcc, s[4:5]
	v_mov_b32_e32 v3, v1
	v_mov_b32_e32 v4, v1
	v_mov_b32_e32 v5, v1
	s_and_saveexec_b64 s[4:5], s[6:7]
	s_cbranch_execz .LBB0_412
	v_add_u32_e32 v4, s20, v8
	v_mov_b64_e32 v[2:3], s[10:11]
	v_mad_i64_i32 v[2:3], s[6:7], v4, s79, v[2:3]
	s_lshl_b32 s40, s42, 1
	v_lshlrev_b32_e32 v4, 3, v6
	v_lshl_add_u64 v[2:3], v[2:3], 0, s[40:41]
	v_ashrrev_i32_e32 v5, 31, v4
	v_lshl_add_u64 v[2:3], v[4:5], 1, v[2:3]
	s_waitcnt vmcnt(0)
	v_mov_b64_e32 v[2:3], v[220:221]
	v_mov_b64_e32 v[4:5], v[222:223]
.LBB0_412:
	s_or_b64 exec, exec, s[4:5]
	v_sub_u32_e32 v7, v15, v7
	v_mul_i32_i24_e32 v6, 0x1880, v6
	v_lshlrev_b32_e32 v7, 1, v7
	v_add3_u32 v6, 0, v6, v7
	s_waitcnt vmcnt(0)
	ds_write_b16 v6, v2 offset:57344
	ds_write_b16_d16_hi v6, v2 offset:58128
	ds_write_b16 v6, v3 offset:58912
	ds_write_b16_d16_hi v6, v3 offset:59696
	ds_write_b16 v6, v4 offset:60480
	ds_write_b16_d16_hi v6, v4 offset:61264
	ds_write_b16 v6, v5 offset:62048
	ds_write_b16_d16_hi v6, v5 offset:62832
	v_mul_hi_i32 v2, v17, s84
	v_lshrrev_b32_e32 v3, 31, v2
	v_ashrrev_i32_e32 v2, 6, v2
	v_add_u32_e32 v6, v2, v3
	v_mul_i32_i24_e32 v7, 0x180, v6
	v_sub_u32_e32 v2, v17, v7
	v_add_u32_e32 v8, s1, v2
	v_mov_b64_e32 v[4:5], v[2:3]
	v_cmp_lt_i32_e32 vcc, -1, v8
	v_cmp_gt_i32_e64 s[4:5], s0, v8
	v_mov_b64_e32 v[2:3], v[0:1]
	s_and_b64 s[6:7], vcc, s[4:5]
	v_mov_b32_e32 v3, v1
	v_mov_b32_e32 v4, v1
	v_mov_b32_e32 v5, v1
	s_and_saveexec_b64 s[4:5], s[6:7]
	s_cbranch_execz .LBB0_414
	v_add_u32_e32 v4, s20, v8
	v_mov_b64_e32 v[2:3], s[10:11]
	v_mad_i64_i32 v[2:3], s[6:7], v4, s79, v[2:3]
	s_lshl_b32 s40, s42, 1
	v_lshlrev_b32_e32 v4, 3, v6
	v_lshl_add_u64 v[2:3], v[2:3], 0, s[40:41]
	v_ashrrev_i32_e32 v5, 31, v4
	v_lshl_add_u64 v[2:3], v[4:5], 1, v[2:3]
	s_waitcnt vmcnt(0)
	v_mov_b64_e32 v[2:3], v[224:225]
	v_mov_b64_e32 v[4:5], v[226:227]
.LBB0_414:
	s_or_b64 exec, exec, s[4:5]
	v_sub_u32_e32 v7, v15, v7
	v_mul_i32_i24_e32 v6, 0x1880, v6
	v_lshlrev_b32_e32 v7, 1, v7
	v_add3_u32 v6, 0, v6, v7
	s_waitcnt vmcnt(0)
	ds_write_b16 v6, v2 offset:58368
	ds_write_b16_d16_hi v6, v2 offset:59152
	ds_write_b16 v6, v3 offset:59936
	ds_write_b16_d16_hi v6, v3 offset:60720
	ds_write_b16 v6, v4 offset:61504
	ds_write_b16_d16_hi v6, v4 offset:62288
	ds_write_b16 v6, v5 offset:63072
	ds_write_b16_d16_hi v6, v5 offset:63856
	v_mul_hi_i32 v2, v18, s84
	v_lshrrev_b32_e32 v3, 31, v2
	v_ashrrev_i32_e32 v2, 6, v2
	v_add_u32_e32 v6, v2, v3
	v_mul_i32_i24_e32 v7, 0x180, v6
	v_sub_u32_e32 v2, v18, v7
	v_add_u32_e32 v8, s1, v2
	v_mov_b64_e32 v[4:5], v[2:3]
	v_cmp_lt_i32_e32 vcc, -1, v8
	v_cmp_gt_i32_e64 s[4:5], s0, v8
	v_mov_b64_e32 v[2:3], v[0:1]
	s_and_b64 s[6:7], vcc, s[4:5]
	v_mov_b32_e32 v3, v1
	v_mov_b32_e32 v4, v1
	v_mov_b32_e32 v5, v1
	s_and_saveexec_b64 s[4:5], s[6:7]
	s_cbranch_execz .LBB0_416
	v_add_u32_e32 v4, s20, v8
	v_mov_b64_e32 v[2:3], s[10:11]
	v_mad_i64_i32 v[2:3], s[6:7], v4, s79, v[2:3]
	s_lshl_b32 s40, s42, 1
	v_lshlrev_b32_e32 v4, 3, v6
	v_lshl_add_u64 v[2:3], v[2:3], 0, s[40:41]
	v_ashrrev_i32_e32 v5, 31, v4
	v_lshl_add_u64 v[2:3], v[4:5], 1, v[2:3]
	s_waitcnt vmcnt(0)
	v_mov_b64_e32 v[2:3], v[228:229]
	v_mov_b64_e32 v[4:5], v[230:231]
.LBB0_416:
	s_or_b64 exec, exec, s[4:5]
	v_sub_u32_e32 v7, v15, v7
	v_mul_i32_i24_e32 v6, 0x1880, v6
	v_lshlrev_b32_e32 v7, 1, v7
	v_add3_u32 v6, 0, v6, v7
	s_waitcnt vmcnt(0)
	ds_write_b16 v6, v2 offset:59392
	ds_write_b16_d16_hi v6, v2 offset:60176
	ds_write_b16 v6, v3 offset:60960
	ds_write_b16_d16_hi v6, v3 offset:61744
	ds_write_b16 v6, v4 offset:62528
	ds_write_b16_d16_hi v6, v4 offset:63312
	ds_write_b16 v6, v5 offset:64096
	ds_write_b16_d16_hi v6, v5 offset:64880
	v_mul_hi_i32 v2, v19, s84
	v_lshrrev_b32_e32 v3, 31, v2
	v_ashrrev_i32_e32 v2, 6, v2
	v_add_u32_e32 v4, v2, v3
	v_mul_i32_i24_e32 v5, 0x180, v4
	v_sub_u32_e32 v2, v19, v5
	v_add_u32_e32 v6, s1, v2
	v_cmp_lt_i32_e32 vcc, -1, v6
	v_cmp_gt_i32_e64 s[4:5], s0, v6
	s_and_b64 s[6:7], vcc, s[4:5]
	v_mov_b32_e32 v2, v1
	v_mov_b32_e32 v3, v1
	s_and_saveexec_b64 s[4:5], s[6:7]
	s_cbranch_execz .LBB0_418
	v_add_u32_e32 v2, s20, v6
	v_mov_b64_e32 v[0:1], s[10:11]
	v_mad_i64_i32 v[0:1], s[6:7], v2, s79, v[0:1]
	s_lshl_b32 s40, s42, 1
	v_lshlrev_b32_e32 v2, 3, v4
	v_lshl_add_u64 v[0:1], v[0:1], 0, s[40:41]
	v_ashrrev_i32_e32 v3, 31, v2
	v_lshl_add_u64 v[0:1], v[2:3], 1, v[0:1]
	s_waitcnt vmcnt(0)
	v_mov_b64_e32 v[0:1], v[232:233]
	v_mov_b64_e32 v[2:3], v[234:235]

.LBB0_504:
	s_or_b64 exec, exec, s[4:5]
	v_sub_u32_e32 v2, 0, v10
	v_bfe_u32 v136, v10, 5, 1
	v_and_b32_e32 v0, 31, v10
	s_ashr_i32 s4, s1, 4
	v_and_b32_e32 v2, 3, v2
	s_and_b32 s1, s4, -4
	v_lshlrev_b32_e32 v139, 4, v136
	v_add_lshl_u32 v0, v2, v0, 1
	s_sub_i32 s7, s1, 31
	v_mul_u32_u24_e32 v3, 0x4440, v2
	s_add_i32 s2, 0, 0x11400
	v_sub_u32_e32 v2, v139, v0
	v_add3_u32 v2, s2, v3, v2
	s_lshl_b32 s2, s7, 8
	v_subrev_u32_e32 v2, s2, v2
	v_add_u32_e32 v4, 0x2140, v2
	s_waitcnt lgkmcnt(0)
	s_barrier
	v_add_u32_e32 v5, 0x2160, v2
	ds_read2_b64 v[108:111], v4 offset1:1
	ds_read2_b64 v[96:99], v5 offset1:1
	v_add_u32_e32 v4, 0x2180, v2
	v_add_u32_e32 v5, 0x21a0, v2
	ds_read2_b64 v[104:107], v4 offset1:1
	ds_read2_b64 v[92:95], v5 offset1:1
	v_add_u32_e32 v4, 0x21c0, v2
	v_add_u32_e32 v5, 0x21e0, v2
	ds_read2_b64 v[100:103], v4 offset1:1
	ds_read2_b64 v[84:87], v5 offset1:1
	v_add_u32_e32 v4, 0x2200, v2
	v_add_u32_e32 v5, 0x2220, v2
	ds_read2_b64 v[116:119], v4 offset1:1
	ds_read2_b64 v[112:115], v5 offset1:1
	v_add_u32_e32 v4, 0x2240, v2
	v_add_u32_e32 v5, 0x2260, v2
	ds_read2_b64 v[88:91], v4 offset1:1
	ds_read2_b64 v[76:79], v5 offset1:1
	v_add_u32_e32 v4, 0x2280, v2
	v_add_u32_e32 v5, 0x22a0, v2
	ds_read2_b64 v[80:83], v4 offset1:1
	ds_read2_b64 v[68:71], v5 offset1:1
	v_add_u32_e32 v4, 0x22c0, v2
	v_add_u32_e32 v2, 0x22e0, v2
	ds_read2_b64 v[72:75], v4 offset1:1
	ds_read2_b64 v[64:67], v2 offset1:1
	s_or_b32 s2, s4, 3
	s_lshl_b32 s4, s4, 8
	v_and_b32_e32 v137, 3, v10
	v_bfe_u32 v138, v10, 2, 3
	v_sub_u32_e32 v0, v3, v0
	s_and_b32 s4, s4, 0xfffffc00
	v_mul_u32_u24_e32 v1, 0x2240, v138
	s_add_i32 s5, 0, 0x11200
	v_mul_u32_u24_e32 v2, 0x110, v137
	v_subrev_u32_e32 v0, s4, v0
	v_mov_b32_e32 v48, 0
	v_add_u32_e32 v140, s5, v139
	v_add3_u32 v141, v1, v2, 0
	v_add_u32_e32 v142, 29, v137
	v_add_u32_e32 v143, 0, v0
	v_mov_b32_e32 v49, v48
	v_mov_b32_e32 v50, v48
	v_mov_b32_e32 v51, v48
	v_mov_b32_e32 v52, v48
	v_mov_b32_e32 v53, v48
	v_mov_b32_e32 v54, v48
	v_mov_b32_e32 v55, v48
	v_mov_b32_e32 v56, v48
	v_mov_b32_e32 v57, v48
	v_mov_b32_e32 v58, v48
	v_mov_b32_e32 v59, v48
	v_mov_b32_e32 v60, v48
	v_mov_b32_e32 v61, v48
	v_mov_b32_e32 v62, v48
	v_mov_b32_e32 v63, v48
	v_mov_b32_e32 v32, v48
	v_mov_b32_e32 v33, v48
	v_mov_b32_e32 v34, v48
	v_mov_b32_e32 v35, v48
	v_mov_b32_e32 v36, v48
	v_mov_b32_e32 v37, v48
	v_mov_b32_e32 v38, v48
	v_mov_b32_e32 v39, v48
	v_mov_b32_e32 v40, v48
	v_mov_b32_e32 v41, v48
	v_mov_b32_e32 v42, v48
	v_mov_b32_e32 v43, v48
	v_mov_b32_e32 v44, v48
	v_mov_b32_e32 v45, v48
	v_mov_b32_e32 v46, v48
	v_mov_b32_e32 v47, v48
	v_mov_b32_e32 v16, v48
	v_mov_b32_e32 v17, v48
	v_mov_b32_e32 v18, v48
	v_mov_b32_e32 v19, v48
	v_mov_b32_e32 v20, v48
	v_mov_b32_e32 v21, v48
	v_mov_b32_e32 v22, v48
	v_mov_b32_e32 v23, v48
	v_mov_b32_e32 v24, v48
	v_mov_b32_e32 v25, v48
	v_mov_b32_e32 v26, v48
	v_mov_b32_e32 v27, v48
	v_mov_b32_e32 v28, v48
	v_mov_b32_e32 v29, v48
	v_mov_b32_e32 v30, v48
	v_mov_b32_e32 v31, v48
	v_mov_b32_e32 v0, v48
	v_mov_b32_e32 v1, v48
	v_mov_b32_e32 v2, v48
	v_mov_b32_e32 v3, v48
	v_mov_b32_e32 v4, v48
	v_mov_b32_e32 v5, v48
	v_mov_b32_e32 v6, v48
	v_mov_b32_e32 v7, v48
	v_mov_b32_e32 v8, v48
	v_mov_b32_e32 v9, v48
	v_mov_b32_e32 v10, v48
	v_mov_b32_e32 v11, v48
	v_mov_b32_e32 v12, v48
	v_mov_b32_e32 v13, v48
	v_mov_b32_e32 v14, v48
	v_mov_b32_e32 v15, v48
	s_cmpk_lt_u32 s1, 16
	s_cbranch_scc1 .Lpb_a
	s_barrier
.Lpb_a:
	s_branch .LBB0_506

.LBB0_506:
	v_add_u32_e32 v120, 2, v142
	v_add_u32_e32 v145, v141, v139
	v_add_u32_e32 v121, 0x20f0, v145
	v_cmp_gt_u32_e32 vcc, 32, v120
	s_nop 1
	v_cndmask_b32_e64 v144, 0, 32, vcc
	v_cndmask_b32_e32 v154, v140, v121, vcc
	v_add_u32_e32 v124, v154, v144
	v_lshl_add_u32 v128, v144, 1, v154
	v_mad_u32_u24 v132, v144, 3, v154
	v_lshl_add_u32 v146, v144, 2, v154
	v_mad_u32_u24 v150, v144, 5, v154
	v_mad_u32_u24 v155, v144, 6, v154
	ds_read_b128 v[120:123], v154
	ds_read_b128 v[124:127], v124
	ds_read_b128 v[128:131], v128
	ds_read_b128 v[132:135], v132
	ds_read_b128 v[146:149], v146
	ds_read_b128 v[150:153], v150
	v_mad_u32_u24 v144, v144, 7, v154
	ds_read_b128 v[154:157], v155
	ds_read_b128 v[174:177], v144
	s_barrier
	s_setprio 1
	s_waitcnt lgkmcnt(7)
	v_mfma_f32_32x32x16_bf16 v[48:63], v[116:119], v[120:123], v[48:63]
	v_mfma_f32_32x32x16_bf16 v[32:47], v[100:103], v[120:123], v[32:47]
	v_mfma_f32_32x32x16_bf16 v[16:31], v[104:107], v[120:123], v[16:31]
	v_mfma_f32_32x32x16_bf16 v[0:15], v[108:111], v[120:123], v[0:15]
	s_waitcnt lgkmcnt(6)
	v_mfma_f32_32x32x16_bf16 v[48:63], v[112:115], v[124:127], v[48:63]
	v_mfma_f32_32x32x16_bf16 v[32:47], v[84:87], v[124:127], v[32:47]
	v_mfma_f32_32x32x16_bf16 v[16:31], v[92:95], v[124:127], v[16:31]
	v_mfma_f32_32x32x16_bf16 v[0:15], v[96:99], v[124:127], v[0:15]
	s_waitcnt lgkmcnt(5)
	v_mfma_f32_32x32x16_bf16 v[48:63], v[88:91], v[128:131], v[48:63]
	v_mfma_f32_32x32x16_bf16 v[32:47], v[116:119], v[128:131], v[32:47]
	v_mfma_f32_32x32x16_bf16 v[16:31], v[100:103], v[128:131], v[16:31]
	v_mfma_f32_32x32x16_bf16 v[0:15], v[104:107], v[128:131], v[0:15]
	s_waitcnt lgkmcnt(4)
	v_mfma_f32_32x32x16_bf16 v[48:63], v[76:79], v[132:135], v[48:63]
	v_mfma_f32_32x32x16_bf16 v[32:47], v[112:115], v[132:135], v[32:47]
	v_mfma_f32_32x32x16_bf16 v[16:31], v[84:87], v[132:135], v[16:31]
	v_mfma_f32_32x32x16_bf16 v[0:15], v[92:95], v[132:135], v[0:15]
	s_waitcnt lgkmcnt(3)
	v_mfma_f32_32x32x16_bf16 v[48:63], v[80:83], v[146:149], v[48:63]
	v_mfma_f32_32x32x16_bf16 v[32:47], v[88:91], v[146:149], v[32:47]
	v_mfma_f32_32x32x16_bf16 v[16:31], v[116:119], v[146:149], v[16:31]
	v_mfma_f32_32x32x16_bf16 v[0:15], v[100:103], v[146:149], v[0:15]
	s_waitcnt lgkmcnt(2)
	v_mfma_f32_32x32x16_bf16 v[48:63], v[68:71], v[150:153], v[48:63]
	v_mfma_f32_32x32x16_bf16 v[32:47], v[76:79], v[150:153], v[32:47]
	v_mfma_f32_32x32x16_bf16 v[16:31], v[112:115], v[150:153], v[16:31]
	v_mfma_f32_32x32x16_bf16 v[0:15], v[84:87], v[150:153], v[0:15]
	s_waitcnt lgkmcnt(1)
	v_mfma_f32_32x32x16_bf16 v[48:63], v[72:75], v[154:157], v[48:63]
	v_mfma_f32_32x32x16_bf16 v[32:47], v[80:83], v[154:157], v[32:47]
	v_mfma_f32_32x32x16_bf16 v[16:31], v[88:91], v[154:157], v[16:31]
	v_mfma_f32_32x32x16_bf16 v[0:15], v[116:119], v[154:157], v[0:15]
	s_waitcnt lgkmcnt(0)
	v_mfma_f32_32x32x16_bf16 v[48:63], v[64:67], v[174:177], v[48:63]
	v_mfma_f32_32x32x16_bf16 v[32:47], v[68:71], v[174:177], v[32:47]
	v_mfma_f32_32x32x16_bf16 v[16:31], v[76:79], v[174:177], v[16:31]
	v_mfma_f32_32x32x16_bf16 v[0:15], v[112:115], v[174:177], v[0:15]
	s_setprio 0
	s_barrier
	s_mov_b64 s[4:5], -1
	s_cmp_ge_i32 s7, s2
	s_nop 8
	v_readfirstlane_b32 s6, v0
	s_cbranch_scc1 .LBB0_505
	v_add_u32_e32 v144, v143, v139
	v_add_u32_e32 v64, 0x15400, v144
	v_add_u32_e32 v69, 0x153e0, v144
	ds_read2_b64 v[64:67], v64 offset1:1
	ds_read2_b64 v[112:115], v69 offset1:1
	v_add_u32_e32 v69, 0x153c0, v144
	v_add_u32_e32 v70, 0x153a0, v144
	v_add_u32_e32 v72, 0x15340, v144
	v_add_u32_e32 v68, 0x15420, v144
	ds_read2_b64 v[124:127], v69 offset1:1
	ds_read2_b64 v[116:119], v70 offset1:1
	v_add_u32_e32 v69, 0x15380, v144
	v_add_u32_e32 v70, 0x15360, v144
	ds_read2_b64 v[128:131], v69 offset1:1
	ds_read2_b64 v[120:123], v70 offset1:1
	ds_read2_b64 v[68:71], v68 offset1:1
	ds_read2_b64 v[132:135], v72 offset1:1
	v_add_u32_e32 v72, 1, v142
	v_add_u32_e32 v73, 0x1fe0, v145
	v_cmp_gt_u32_e32 vcc, 32, v72
	s_nop 1
	v_cndmask_b32_e64 v154, 0, 32, vcc
	v_cndmask_b32_e32 v155, v140, v73, vcc
	v_add_u32_e32 v76, v155, v154
	v_lshl_add_u32 v80, v154, 1, v155
	v_mad_u32_u24 v88, v154, 3, v155
	v_lshl_add_u32 v146, v154, 2, v155
	v_mad_u32_u24 v150, v154, 5, v155
	v_mad_u32_u24 v156, v154, 6, v155
	ds_read_b128 v[72:75], v155
	ds_read_b128 v[76:79], v76
	ds_read_b128 v[80:83], v80
	ds_read_b128 v[88:91], v88
	ds_read_b128 v[146:149], v146
	ds_read_b128 v[150:153], v150
	v_mad_u32_u24 v158, v154, 7, v155
	ds_read_b128 v[154:157], v156
	ds_read_b128 v[174:177], v158
	s_barrier
	s_setprio 1
	s_waitcnt lgkmcnt(7)
	v_mfma_f32_32x32x16_bf16 v[48:63], v[64:67], v[72:75], v[48:63]
	v_mfma_f32_32x32x16_bf16 v[32:47], v[124:127], v[72:75], v[32:47]
	v_mfma_f32_32x32x16_bf16 v[16:31], v[128:131], v[72:75], v[16:31]
	v_mfma_f32_32x32x16_bf16 v[0:15], v[132:135], v[72:75], v[0:15]
	s_waitcnt lgkmcnt(6)
	v_mfma_f32_32x32x16_bf16 v[48:63], v[68:71], v[76:79], v[48:63]
	v_mfma_f32_32x32x16_bf16 v[32:47], v[112:115], v[76:79], v[32:47]
	v_mfma_f32_32x32x16_bf16 v[16:31], v[116:119], v[76:79], v[16:31]
	v_mfma_f32_32x32x16_bf16 v[0:15], v[120:123], v[76:79], v[0:15]
	s_waitcnt lgkmcnt(5)
	v_mfma_f32_32x32x16_bf16 v[48:63], v[108:111], v[80:83], v[48:63]
	v_mfma_f32_32x32x16_bf16 v[32:47], v[64:67], v[80:83], v[32:47]
	v_mfma_f32_32x32x16_bf16 v[16:31], v[124:127], v[80:83], v[16:31]
	v_mfma_f32_32x32x16_bf16 v[0:15], v[128:131], v[80:83], v[0:15]
	s_waitcnt lgkmcnt(4)
	v_mfma_f32_32x32x16_bf16 v[48:63], v[96:99], v[88:91], v[48:63]
	v_mfma_f32_32x32x16_bf16 v[32:47], v[68:71], v[88:91], v[32:47]
	v_mfma_f32_32x32x16_bf16 v[16:31], v[112:115], v[88:91], v[16:31]
	v_mfma_f32_32x32x16_bf16 v[0:15], v[116:119], v[88:91], v[0:15]
	s_waitcnt lgkmcnt(3)
	v_mfma_f32_32x32x16_bf16 v[48:63], v[104:107], v[146:149], v[48:63]
	v_mfma_f32_32x32x16_bf16 v[32:47], v[108:111], v[146:149], v[32:47]
	v_mfma_f32_32x32x16_bf16 v[16:31], v[64:67], v[146:149], v[16:31]
	v_mfma_f32_32x32x16_bf16 v[0:15], v[124:127], v[146:149], v[0:15]
	s_waitcnt lgkmcnt(2)
	v_mfma_f32_32x32x16_bf16 v[48:63], v[92:95], v[150:153], v[48:63]
	v_mfma_f32_32x32x16_bf16 v[32:47], v[96:99], v[150:153], v[32:47]
	v_mfma_f32_32x32x16_bf16 v[16:31], v[68:71], v[150:153], v[16:31]
	v_mfma_f32_32x32x16_bf16 v[0:15], v[112:115], v[150:153], v[0:15]
	s_waitcnt lgkmcnt(1)
	v_mfma_f32_32x32x16_bf16 v[48:63], v[100:103], v[154:157], v[48:63]
	v_mfma_f32_32x32x16_bf16 v[32:47], v[104:107], v[154:157], v[32:47]
	v_mfma_f32_32x32x16_bf16 v[16:31], v[108:111], v[154:157], v[16:31]
	v_mfma_f32_32x32x16_bf16 v[0:15], v[64:67], v[154:157], v[0:15]
	s_waitcnt lgkmcnt(0)
	v_mfma_f32_32x32x16_bf16 v[48:63], v[84:87], v[174:177], v[48:63]
	v_mfma_f32_32x32x16_bf16 v[32:47], v[92:95], v[174:177], v[32:47]
	v_mfma_f32_32x32x16_bf16 v[16:31], v[96:99], v[174:177], v[16:31]
	v_mfma_f32_32x32x16_bf16 v[0:15], v[68:71], v[174:177], v[0:15]
	s_setprio 0
	s_barrier
	s_add_i32 s6, s7, 2
	s_cmp_le_i32 s6, s2
	s_nop 8
	v_readfirstlane_b32 s6, v0
	s_cbranch_scc0 .LBB0_505
	v_add_u32_e32 v88, 0x15240, v144
	v_add_u32_e32 v89, 0x15320, v144
	v_add_u32_e32 v64, 0x15300, v144
	v_add_u32_e32 v65, 0x152e0, v144
	v_add_u32_e32 v68, 0x152c0, v144
	v_add_u32_e32 v69, 0x152a0, v144
	v_add_u32_e32 v76, 0x15280, v144
	v_add_u32_e32 v77, 0x15260, v144
	v_add_u32_e32 v96, 0x1ed0, v145
	v_cmp_gt_u32_e32 vcc, 32, v142
	ds_read2_b64 v[84:87], v64 offset1:1
	ds_read2_b64 v[64:67], v65 offset1:1
	ds_read2_b64 v[72:75], v68 offset1:1
	ds_read2_b64 v[68:71], v69 offset1:1
	ds_read2_b64 v[80:83], v76 offset1:1
	ds_read2_b64 v[76:79], v77 offset1:1
	ds_read2_b64 v[92:95], v89 offset1:1
	ds_read2_b64 v[88:91], v88 offset1:1
	v_cndmask_b32_e64 v145, 0, 32, vcc
	v_cndmask_b32_e32 v154, v140, v96, vcc
	v_add_u32_e32 v100, v154, v145
	v_lshl_add_u32 v104, v145, 1, v154
	v_mad_u32_u24 v108, v145, 3, v154
	v_lshl_add_u32 v146, v145, 2, v154
	v_mad_u32_u24 v150, v145, 5, v154
	v_mad_u32_u24 v155, v145, 6, v154
	ds_read_b128 v[96:99], v154
	ds_read_b128 v[100:103], v100
	ds_read_b128 v[104:107], v104
	ds_read_b128 v[108:111], v108
	ds_read_b128 v[146:149], v146
	ds_read_b128 v[150:153], v150
	v_mad_u32_u24 v145, v145, 7, v154
	ds_read_b128 v[154:157], v155
	ds_read_b128 v[174:177], v145
	s_barrier
	s_setprio 1
	s_waitcnt lgkmcnt(7)
	v_mfma_f32_32x32x16_bf16 v[48:63], v[84:87], v[96:99], v[48:63]
	v_mfma_f32_32x32x16_bf16 v[32:47], v[72:75], v[96:99], v[32:47]
	v_mfma_f32_32x32x16_bf16 v[16:31], v[80:83], v[96:99], v[16:31]
	v_mfma_f32_32x32x16_bf16 v[0:15], v[88:91], v[96:99], v[0:15]
	s_waitcnt lgkmcnt(6)
	v_mfma_f32_32x32x16_bf16 v[48:63], v[92:95], v[100:103], v[48:63]
	v_mfma_f32_32x32x16_bf16 v[32:47], v[64:67], v[100:103], v[32:47]
	v_mfma_f32_32x32x16_bf16 v[16:31], v[68:71], v[100:103], v[16:31]
	v_mfma_f32_32x32x16_bf16 v[0:15], v[76:79], v[100:103], v[0:15]
	s_waitcnt lgkmcnt(5)
	v_mfma_f32_32x32x16_bf16 v[48:63], v[132:135], v[104:107], v[48:63]
	v_mfma_f32_32x32x16_bf16 v[32:47], v[84:87], v[104:107], v[32:47]
	v_mfma_f32_32x32x16_bf16 v[16:31], v[72:75], v[104:107], v[16:31]
	v_mfma_f32_32x32x16_bf16 v[0:15], v[80:83], v[104:107], v[0:15]
	s_waitcnt lgkmcnt(4)
	v_mfma_f32_32x32x16_bf16 v[48:63], v[120:123], v[108:111], v[48:63]
	v_mfma_f32_32x32x16_bf16 v[32:47], v[92:95], v[108:111], v[32:47]
	v_mfma_f32_32x32x16_bf16 v[16:31], v[64:67], v[108:111], v[16:31]
	v_mfma_f32_32x32x16_bf16 v[0:15], v[68:71], v[108:111], v[0:15]
	s_waitcnt lgkmcnt(3)
	v_mfma_f32_32x32x16_bf16 v[48:63], v[128:131], v[146:149], v[48:63]
	v_mfma_f32_32x32x16_bf16 v[32:47], v[132:135], v[146:149], v[32:47]
	v_mfma_f32_32x32x16_bf16 v[16:31], v[84:87], v[146:149], v[16:31]
	v_mfma_f32_32x32x16_bf16 v[0:15], v[72:75], v[146:149], v[0:15]
	s_waitcnt lgkmcnt(2)
	v_mfma_f32_32x32x16_bf16 v[48:63], v[116:119], v[150:153], v[48:63]
	v_mfma_f32_32x32x16_bf16 v[32:47], v[120:123], v[150:153], v[32:47]
	v_mfma_f32_32x32x16_bf16 v[16:31], v[92:95], v[150:153], v[16:31]
	v_mfma_f32_32x32x16_bf16 v[0:15], v[64:67], v[150:153], v[0:15]
	s_waitcnt lgkmcnt(1)
	v_mfma_f32_32x32x16_bf16 v[48:63], v[124:127], v[154:157], v[48:63]
	v_mfma_f32_32x32x16_bf16 v[32:47], v[128:131], v[154:157], v[32:47]
	v_mfma_f32_32x32x16_bf16 v[16:31], v[132:135], v[154:157], v[16:31]
	v_mfma_f32_32x32x16_bf16 v[0:15], v[84:87], v[154:157], v[0:15]
	s_waitcnt lgkmcnt(0)
	v_mfma_f32_32x32x16_bf16 v[48:63], v[112:115], v[174:177], v[48:63]
	v_mfma_f32_32x32x16_bf16 v[32:47], v[116:119], v[174:177], v[32:47]
	v_mfma_f32_32x32x16_bf16 v[16:31], v[120:123], v[174:177], v[16:31]
	v_mfma_f32_32x32x16_bf16 v[0:15], v[92:95], v[174:177], v[0:15]
	s_setprio 0
	s_barrier
	v_add_u32_e32 v84, 0x15140, v144
	v_add_u32_e32 v85, 0x15160, v144
	ds_read2_b64 v[108:111], v84 offset1:1
	ds_read2_b64 v[96:99], v85 offset1:1
	v_add_u32_e32 v84, 0x15180, v144
	v_add_u32_e32 v85, 0x151a0, v144
	ds_read2_b64 v[104:107], v84 offset1:1
	ds_read2_b64 v[92:95], v85 offset1:1
	v_add_u32_e32 v84, 0x151c0, v144
	v_add_u32_e32 v85, 0x151e0, v144
	v_add_u32_e32 v112, 0x15200, v144
	v_add_u32_e32 v113, 0x15220, v144
	ds_read2_b64 v[100:103], v84 offset1:1
	ds_read2_b64 v[84:87], v85 offset1:1
	ds_read2_b64 v[116:119], v112 offset1:1
	ds_read2_b64 v[112:115], v113 offset1:1
	s_add_i32 s6, s7, 3
	s_cmp_gt_i32 s6, s2
	v_add_u32_e32 v141, 0xfffffcd0, v141
	v_add_u32_e32 v142, -3, v142
	v_add_u32_e32 v143, 0xfffffd00, v143
	s_cselect_b64 s[4:5], -1, 0
	s_and_b64 vcc, exec, s[4:5]
	s_mov_b32 s7, s6
	s_cbranch_vccz .LBB0_506
.LBB0_509:
	s_cmpk_lt_u32 s1, 16
	s_cbranch_scc0 .Lpb_b
	s_barrier

.LBB0_522:
	s_or_b64 exec, exec, s[4:5]
	s_bfe_u32 s1, s0, 0x20006
	s_lshl_b32 s6, s1, 5
	v_sub_u32_e32 v0, 0, v34
	v_bfe_u32 v137, v34, 5, 1
	v_and_b32_e32 v12, 31, v34
	s_or_b32 s2, s6, 0xffffff81
	v_and_b32_e32 v13, 3, v0
	s_sub_i32 s4, s6, 47
	s_sub_i32 s5, s6, 48
	s_or_b32 s7, s6, 31
	v_lshlrev_b32_e32 v138, 4, v137
	v_add_lshl_u32 v14, v13, v12, 1
	s_cmpk_lt_u32 s0, 0x100
	v_sub_u32_e32 v1, v138, v14
	s_cselect_b32 s8, s2, s4
	v_add_u32_e32 v1, 0, v1
	s_cselect_b32 s2, s5, s7
	s_lshl_b32 s7, s8, 8
	v_lshlrev_b32_e32 v139, 4, v0
	v_subrev_u32_e32 v0, s7, v1
	v_add_u32_e32 v15, 0x8a00, v0
	v_add_u32_e32 v0, 0x8140, v15
	s_waitcnt lgkmcnt(0)
	s_barrier
	ds_read2_b64 v[0:3], v0 offset1:1
	v_add_u32_e32 v16, 0x8000, v15
	v_add_u32_e32 v8, 0x8160, v15
	ds_read2_b64 v[4:7], v16 offset0:42 offset1:46
	ds_read2_b64 v[8:11], v8 offset1:1
	v_cmp_gt_u32_e64 s[4:5], 2, v13
	s_mul_i32 s9, s1, 0x2200
	v_or_b32_e32 v140, s6, v12
	s_waitcnt lgkmcnt(2)
	v_cndmask_b32_e64 v0, v1, v0, s[4:5]
	v_cndmask_b32_e64 v1, v2, v1, s[4:5]
	v_cndmask_b32_e64 v2, v3, v2, s[4:5]
	s_waitcnt lgkmcnt(1)
	v_cndmask_b32_e64 v3, v4, v3, s[4:5]
	v_cndmask_b32_e64 v4, v5, v4, s[4:5]
	v_alignbit_b32 v64, v1, v0, v139
	v_alignbit_b32 v65, v2, v1, v139
	s_waitcnt lgkmcnt(0)
	v_cndmask_b32_e64 v0, v9, v8, s[4:5]
	v_cndmask_b32_e64 v1, v10, v9, s[4:5]
	v_alignbit_b32 v66, v3, v2, v139
	v_alignbit_b32 v67, v4, v3, v139
	v_cndmask_b32_e64 v2, v11, v10, s[4:5]
	v_cndmask_b32_e64 v4, v6, v11, s[4:5]
	v_alignbit_b32 v68, v1, v0, v139
	v_add_u32_e32 v0, 0x8180, v15
	v_cndmask_b32_e64 v5, v7, v6, s[4:5]
	v_alignbit_b32 v69, v2, v1, v139
	v_alignbit_b32 v70, v4, v2, v139
	ds_read2_b64 v[0:3], v0 offset1:1
	v_add_u32_e32 v8, 0x81a0, v15
	v_alignbit_b32 v71, v5, v4, v139
	ds_read2_b64 v[4:7], v16 offset0:50 offset1:54
	ds_read2_b64 v[8:11], v8 offset1:1
	s_waitcnt lgkmcnt(2)
	v_cndmask_b32_e64 v0, v1, v0, s[4:5]
	v_cndmask_b32_e64 v1, v2, v1, s[4:5]
	v_cndmask_b32_e64 v2, v3, v2, s[4:5]
	s_waitcnt lgkmcnt(1)
	v_cndmask_b32_e64 v3, v4, v3, s[4:5]
	v_cndmask_b32_e64 v4, v5, v4, s[4:5]
	v_alignbit_b32 v72, v1, v0, v139
	v_alignbit_b32 v73, v2, v1, v139
	s_waitcnt lgkmcnt(0)
	v_cndmask_b32_e64 v0, v9, v8, s[4:5]
	v_cndmask_b32_e64 v1, v10, v9, s[4:5]
	v_alignbit_b32 v74, v3, v2, v139
	v_alignbit_b32 v75, v4, v3, v139
	v_cndmask_b32_e64 v2, v11, v10, s[4:5]
	v_cndmask_b32_e64 v4, v6, v11, s[4:5]
	v_alignbit_b32 v76, v1, v0, v139
	v_add_u32_e32 v0, 0x81c0, v15
	v_cndmask_b32_e64 v5, v7, v6, s[4:5]
	v_alignbit_b32 v77, v2, v1, v139
	v_alignbit_b32 v78, v4, v2, v139
	ds_read2_b64 v[0:3], v0 offset1:1
	v_add_u32_e32 v8, 0x81e0, v15
	v_alignbit_b32 v79, v5, v4, v139
	ds_read2_b64 v[4:7], v16 offset0:58 offset1:62
	ds_read2_b64 v[8:11], v8 offset1:1
	s_waitcnt lgkmcnt(2)
	v_cndmask_b32_e64 v0, v1, v0, s[4:5]
	v_cndmask_b32_e64 v1, v2, v1, s[4:5]
	v_cndmask_b32_e64 v2, v3, v2, s[4:5]
	s_waitcnt lgkmcnt(1)
	v_cndmask_b32_e64 v3, v4, v3, s[4:5]
	v_cndmask_b32_e64 v4, v5, v4, s[4:5]
	v_alignbit_b32 v80, v1, v0, v139
	v_alignbit_b32 v81, v2, v1, v139
	s_waitcnt lgkmcnt(0)
	v_cndmask_b32_e64 v0, v9, v8, s[4:5]
	v_cndmask_b32_e64 v1, v10, v9, s[4:5]
	v_alignbit_b32 v82, v3, v2, v139
	v_alignbit_b32 v83, v4, v3, v139
	v_cndmask_b32_e64 v2, v11, v10, s[4:5]
	v_cndmask_b32_e64 v4, v6, v11, s[4:5]
	v_alignbit_b32 v84, v1, v0, v139
	v_add_u32_e32 v0, 0x8200, v15
	v_cndmask_b32_e64 v5, v7, v6, s[4:5]
	v_alignbit_b32 v85, v2, v1, v139
	v_alignbit_b32 v86, v4, v2, v139
	ds_read2_b64 v[0:3], v0 offset1:1
	v_add_u32_e32 v8, 0x8220, v15
	v_alignbit_b32 v87, v5, v4, v139
	ds_read2_b64 v[4:7], v16 offset0:66 offset1:70
	ds_read2_b64 v[8:11], v8 offset1:1
	s_waitcnt lgkmcnt(2)
	v_cndmask_b32_e64 v0, v1, v0, s[4:5]
	v_cndmask_b32_e64 v1, v2, v1, s[4:5]
	v_cndmask_b32_e64 v2, v3, v2, s[4:5]
	s_waitcnt lgkmcnt(1)
	v_cndmask_b32_e64 v3, v4, v3, s[4:5]
	v_cndmask_b32_e64 v4, v5, v4, s[4:5]
	v_alignbit_b32 v112, v1, v0, v139
	v_alignbit_b32 v113, v2, v1, v139
	s_waitcnt lgkmcnt(0)
	v_cndmask_b32_e64 v0, v9, v8, s[4:5]
	v_cndmask_b32_e64 v1, v10, v9, s[4:5]
	v_alignbit_b32 v114, v3, v2, v139
	v_alignbit_b32 v115, v4, v3, v139
	v_cndmask_b32_e64 v2, v11, v10, s[4:5]
	v_cndmask_b32_e64 v4, v6, v11, s[4:5]
	v_alignbit_b32 v116, v1, v0, v139
	v_add_u32_e32 v0, 0x8240, v15
	v_cndmask_b32_e64 v5, v7, v6, s[4:5]
	v_alignbit_b32 v117, v2, v1, v139
	v_alignbit_b32 v118, v4, v2, v139
	ds_read2_b64 v[0:3], v0 offset1:1
	v_add_u32_e32 v8, 0x8260, v15
	v_alignbit_b32 v119, v5, v4, v139
	ds_read2_b64 v[4:7], v16 offset0:74 offset1:78
	ds_read2_b64 v[8:11], v8 offset1:1
	s_waitcnt lgkmcnt(2)
	v_cndmask_b32_e64 v0, v1, v0, s[4:5]
	v_cndmask_b32_e64 v1, v2, v1, s[4:5]
	v_cndmask_b32_e64 v2, v3, v2, s[4:5]
	s_waitcnt lgkmcnt(1)
	v_cndmask_b32_e64 v3, v4, v3, s[4:5]
	v_cndmask_b32_e64 v4, v5, v4, s[4:5]
	v_alignbit_b32 v108, v1, v0, v139
	v_alignbit_b32 v109, v2, v1, v139
	s_waitcnt lgkmcnt(0)
	v_cndmask_b32_e64 v0, v9, v8, s[4:5]
	v_cndmask_b32_e64 v1, v10, v9, s[4:5]
	v_alignbit_b32 v110, v3, v2, v139
	v_alignbit_b32 v111, v4, v3, v139
	v_cndmask_b32_e64 v2, v11, v10, s[4:5]
	v_cndmask_b32_e64 v4, v6, v11, s[4:5]
	v_alignbit_b32 v96, v1, v0, v139
	v_add_u32_e32 v0, 0x8280, v15
	v_cndmask_b32_e64 v5, v7, v6, s[4:5]
	v_alignbit_b32 v97, v2, v1, v139
	v_alignbit_b32 v98, v4, v2, v139
	ds_read2_b64 v[0:3], v0 offset1:1
	v_add_u32_e32 v8, 0x82a0, v15
	v_alignbit_b32 v99, v5, v4, v139
	ds_read2_b64 v[4:7], v16 offset0:82 offset1:86
	ds_read2_b64 v[8:11], v8 offset1:1
	s_waitcnt lgkmcnt(2)
	v_cndmask_b32_e64 v0, v1, v0, s[4:5]
	v_cndmask_b32_e64 v1, v2, v1, s[4:5]
	v_cndmask_b32_e64 v2, v3, v2, s[4:5]
	s_waitcnt lgkmcnt(1)
	v_cndmask_b32_e64 v3, v4, v3, s[4:5]
	v_cndmask_b32_e64 v4, v5, v4, s[4:5]
	v_alignbit_b32 v104, v1, v0, v139
	v_alignbit_b32 v105, v2, v1, v139
	s_waitcnt lgkmcnt(0)
	v_cndmask_b32_e64 v0, v9, v8, s[4:5]
	v_cndmask_b32_e64 v1, v10, v9, s[4:5]
	v_alignbit_b32 v106, v3, v2, v139
	v_alignbit_b32 v107, v4, v3, v139
	v_cndmask_b32_e64 v2, v11, v10, s[4:5]
	v_cndmask_b32_e64 v4, v6, v11, s[4:5]
	v_alignbit_b32 v92, v1, v0, v139
	v_add_u32_e32 v0, 0x82c0, v15
	v_alignbit_b32 v93, v2, v1, v139
	v_alignbit_b32 v94, v4, v2, v139
	ds_read2_b64 v[0:3], v0 offset1:1
	v_add_u32_e32 v8, 0x82e0, v15
	ds_read2_b64 v[8:11], v8 offset1:1
	v_cndmask_b32_e64 v5, v7, v6, s[4:5]
	v_alignbit_b32 v95, v5, v4, v139
	ds_read2_b64 v[4:7], v16 offset0:90 offset1:94
	s_waitcnt lgkmcnt(2)
	v_cndmask_b32_e64 v0, v1, v0, s[4:5]
	v_cndmask_b32_e64 v1, v2, v1, s[4:5]
	v_cndmask_b32_e64 v2, v3, v2, s[4:5]
	v_alignbit_b32 v100, v1, v0, v139
	v_alignbit_b32 v101, v2, v1, v139
	s_waitcnt lgkmcnt(1)
	v_cndmask_b32_e64 v0, v9, v8, s[4:5]
	v_cndmask_b32_e64 v1, v10, v9, s[4:5]
	v_alignbit_b32 v88, v1, v0, v139
	v_add_u32_e32 v0, 0, v138
	v_add_u32_e32 v141, 0x8800, v0
	v_mov_b32_e32 v0, s9
	v_mad_u32_u24 v0, v12, s3, v0
	s_mul_i32 s9, s8, 0x110
	s_waitcnt lgkmcnt(0)
	v_cndmask_b32_e64 v3, v4, v3, s[4:5]
	v_cndmask_b32_e64 v4, v5, v4, s[4:5]
	v_subrev_u32_e32 v0, s9, v0
	v_alignbit_b32 v102, v3, v2, v139
	v_alignbit_b32 v103, v4, v3, v139
	v_cndmask_b32_e64 v2, v11, v10, s[4:5]
	v_cndmask_b32_e64 v3, v6, v11, s[4:5]
	v_cndmask_b32_e64 v4, v7, v6, s[4:5]
	v_add_u32_e32 v142, 0, v0
	v_subrev_u32_e32 v143, s8, v140
	v_or_b32_e32 v0, s7, v14
	v_mov_b32_e32 v48, 0
	v_and_b32_e32 v136, 63, v34
	v_alignbit_b32 v89, v2, v1, v139
	v_alignbit_b32 v90, v3, v2, v139
	v_alignbit_b32 v91, v4, v3, v139
	v_mad_i32_i24 v144, v143, s3, 0
	v_sub_u32_e32 v145, 0, v0
	v_mov_b32_e32 v49, v48
	v_mov_b32_e32 v50, v48
	v_mov_b32_e32 v51, v48
	v_mov_b32_e32 v52, v48
	v_mov_b32_e32 v53, v48
	v_mov_b32_e32 v54, v48
	v_mov_b32_e32 v55, v48
	v_mov_b32_e32 v56, v48
	v_mov_b32_e32 v57, v48
	v_mov_b32_e32 v58, v48
	v_mov_b32_e32 v59, v48
	v_mov_b32_e32 v60, v48
	v_mov_b32_e32 v61, v48
	v_mov_b32_e32 v62, v48
	v_mov_b32_e32 v63, v48
	v_mov_b32_e32 v32, v48
	v_mov_b32_e32 v33, v48
	v_mov_b32_e32 v34, v48
	v_mov_b32_e32 v35, v48
	v_mov_b32_e32 v36, v48
	v_mov_b32_e32 v37, v48
	v_mov_b32_e32 v38, v48
	v_mov_b32_e32 v39, v48
	v_mov_b32_e32 v40, v48
	v_mov_b32_e32 v41, v48
	v_mov_b32_e32 v42, v48
	v_mov_b32_e32 v43, v48
	v_mov_b32_e32 v44, v48
	v_mov_b32_e32 v45, v48
	v_mov_b32_e32 v46, v48
	v_mov_b32_e32 v47, v48
	v_mov_b32_e32 v16, v48
	v_mov_b32_e32 v17, v48
	v_mov_b32_e32 v18, v48
	v_mov_b32_e32 v19, v48
	v_mov_b32_e32 v20, v48
	v_mov_b32_e32 v21, v48
	v_mov_b32_e32 v22, v48
	v_mov_b32_e32 v23, v48
	v_mov_b32_e32 v24, v48
	v_mov_b32_e32 v25, v48
	v_mov_b32_e32 v26, v48
	v_mov_b32_e32 v27, v48
	v_mov_b32_e32 v28, v48
	v_mov_b32_e32 v29, v48
	v_mov_b32_e32 v30, v48
	v_mov_b32_e32 v31, v48
	v_mov_b32_e32 v0, v48
	v_mov_b32_e32 v1, v48
	v_mov_b32_e32 v2, v48
	v_mov_b32_e32 v3, v48
	v_mov_b32_e32 v4, v48
	v_mov_b32_e32 v5, v48
	v_mov_b32_e32 v6, v48
	v_mov_b32_e32 v7, v48
	v_mov_b32_e32 v8, v48
	v_mov_b32_e32 v9, v48
	v_mov_b32_e32 v10, v48
	v_mov_b32_e32 v11, v48
	v_mov_b32_e32 v12, v48
	v_mov_b32_e32 v13, v48
	v_mov_b32_e32 v14, v48
	v_mov_b32_e32 v15, v48
	v_cndmask_b32_e64 v239, 4, 0, s[4:5]
	s_cmpk_lt_u32 s0, 0x100
	s_cbranch_scc1 .Lsb_a
	s_barrier

.LBB0_524:
	v_add_u32_e32 v120, v144, v138
	v_cmp_gt_u32_e32 vcc, s96, v143
	s_nop 1
	v_cndmask_b32_e64 v154, 0, 32, vcc
	v_cndmask_b32_e32 v155, v141, v120, vcc
	v_add_u32_e32 v124, v155, v154
	v_lshl_add_u32 v128, v154, 1, v155
	v_mad_u32_u24 v132, v154, 3, v155
	v_lshl_add_u32 v146, v154, 2, v155
	v_mad_u32_u24 v150, v154, 5, v155
	v_mad_u32_u24 v156, v154, 6, v155
	ds_read_b128 v[120:123], v155
	ds_read_b128 v[124:127], v124
	ds_read_b128 v[128:131], v128
	ds_read_b128 v[132:135], v132
	ds_read_b128 v[146:149], v146
	ds_read_b128 v[150:153], v150
	v_mad_u32_u24 v158, v154, 7, v155
	ds_read_b128 v[154:157], v156
	ds_read_b128 v[174:177], v158
	s_barrier
	s_setprio 1
	s_waitcnt lgkmcnt(7)
	v_mfma_f32_32x32x16_bf16 v[48:63], v[112:115], v[120:123], v[48:63]
	v_mfma_f32_32x32x16_bf16 v[32:47], v[80:83], v[120:123], v[32:47]
	v_mfma_f32_32x32x16_bf16 v[16:31], v[72:75], v[120:123], v[16:31]
	v_mfma_f32_32x32x16_bf16 v[0:15], v[64:67], v[120:123], v[0:15]
	s_waitcnt lgkmcnt(6)
	v_mfma_f32_32x32x16_bf16 v[48:63], v[116:119], v[124:127], v[48:63]
	v_mfma_f32_32x32x16_bf16 v[32:47], v[84:87], v[124:127], v[32:47]
	v_mfma_f32_32x32x16_bf16 v[16:31], v[76:79], v[124:127], v[16:31]
	v_mfma_f32_32x32x16_bf16 v[0:15], v[68:71], v[124:127], v[0:15]
	s_waitcnt lgkmcnt(5)
	v_mfma_f32_32x32x16_bf16 v[48:63], v[108:111], v[128:131], v[48:63]
	v_mfma_f32_32x32x16_bf16 v[32:47], v[112:115], v[128:131], v[32:47]
	v_mfma_f32_32x32x16_bf16 v[16:31], v[80:83], v[128:131], v[16:31]
	v_mfma_f32_32x32x16_bf16 v[0:15], v[72:75], v[128:131], v[0:15]
	s_waitcnt lgkmcnt(4)
	v_mfma_f32_32x32x16_bf16 v[48:63], v[96:99], v[132:135], v[48:63]
	v_mfma_f32_32x32x16_bf16 v[32:47], v[116:119], v[132:135], v[32:47]
	v_mfma_f32_32x32x16_bf16 v[16:31], v[84:87], v[132:135], v[16:31]
	v_mfma_f32_32x32x16_bf16 v[0:15], v[76:79], v[132:135], v[0:15]
	s_waitcnt lgkmcnt(3)
	v_mfma_f32_32x32x16_bf16 v[48:63], v[104:107], v[146:149], v[48:63]
	v_mfma_f32_32x32x16_bf16 v[32:47], v[108:111], v[146:149], v[32:47]
	v_mfma_f32_32x32x16_bf16 v[16:31], v[112:115], v[146:149], v[16:31]
	v_mfma_f32_32x32x16_bf16 v[0:15], v[80:83], v[146:149], v[0:15]
	s_waitcnt lgkmcnt(2)
	v_mfma_f32_32x32x16_bf16 v[48:63], v[92:95], v[150:153], v[48:63]
	v_mfma_f32_32x32x16_bf16 v[32:47], v[96:99], v[150:153], v[32:47]
	v_mfma_f32_32x32x16_bf16 v[16:31], v[116:119], v[150:153], v[16:31]
	v_mfma_f32_32x32x16_bf16 v[0:15], v[84:87], v[150:153], v[0:15]
	s_waitcnt lgkmcnt(1)
	v_mfma_f32_32x32x16_bf16 v[48:63], v[100:103], v[154:157], v[48:63]
	v_mfma_f32_32x32x16_bf16 v[32:47], v[104:107], v[154:157], v[32:47]
	v_mfma_f32_32x32x16_bf16 v[16:31], v[108:111], v[154:157], v[16:31]
	v_mfma_f32_32x32x16_bf16 v[0:15], v[112:115], v[154:157], v[0:15]
	s_waitcnt lgkmcnt(0)
	v_mfma_f32_32x32x16_bf16 v[48:63], v[88:91], v[174:177], v[48:63]
	v_mfma_f32_32x32x16_bf16 v[32:47], v[92:95], v[174:177], v[32:47]
	v_mfma_f32_32x32x16_bf16 v[16:31], v[96:99], v[174:177], v[16:31]
	v_mfma_f32_32x32x16_bf16 v[0:15], v[116:119], v[174:177], v[0:15]
	s_setprio 0
	s_barrier
	s_mov_b64 s[6:7], -1
	s_cmp_ge_i32 s8, s2
	s_cbranch_scc1 .LBB0_523
	v_add_u32_e32 v146, v145, v138
	v_add_u32_e32 v110, v142, v138
	v_add_u32_e32 v97, -1, v143
	v_add_u32_e32 v98, 0xfffffef0, v110
	v_cmp_gt_u32_e32 vcc, s96, v97
	v_cndmask_b32_e64 v97, 0, 32, vcc
	v_cndmask_b32_e32 v98, v141, v98, vcc
	v_add_u32_e32 v104, v98, v97
	v_lshl_add_u32 v111, v97, 1, v98
	ds_read_b128 v[100:103], v98
	ds_read_b128 v[104:107], v104
	v_mad_u32_u24 v134, v97, 3, v98
	ds_read_b128 v[148:151], v111
	ds_read_b128 v[152:155], v134
	v_lshl_add_u32 v111, v97, 2, v98
	v_mad_u32_u24 v134, v97, 5, v98
	ds_read_b128 v[156:159], v111
	ds_read_b128 v[174:177], v134
	v_mad_u32_u24 v111, v97, 6, v98
	v_mad_u32_u24 v97, v97, 7, v98
	ds_read_b128 v[178:181], v111
	ds_read_b128 v[182:185], v97
	v_add_u32_e32 v238, 0x10a40, v146
	ds_read2_b64 v[186:189], v238 offset0:0 offset1:1
	ds_read_b64 v[190:191], v238 offset:16
	ds_read2_b64 v[192:195], v238 offset0:4 offset1:5
	ds_read_b64 v[196:197], v238 offset:48
	ds_read2_b64 v[198:201], v238 offset0:8 offset1:9
	ds_read_b64 v[202:203], v238 offset:80
	s_waitcnt lgkmcnt(4)
	ds_read2_b64 v[204:207], v238 offset0:12 offset1:13
	ds_read_b64 v[208:209], v238 offset:112
	v_cndmask_b32_e64 v186, v187, v186, s[4:5]
	v_cndmask_b32_e64 v187, v188, v187, s[4:5]
	v_cndmask_b32_e64 v188, v189, v188, s[4:5]
	v_cndmask_b32_e64 v189, v190, v189, s[4:5]
	v_cndmask_b32_e64 v190, v191, v190, s[4:5]
	v_alignbit_b32 v132, v187, v186, v139
	v_alignbit_b32 v133, v188, v187, v139
	v_alignbit_b32 v134, v189, v188, v139
	v_alignbit_b32 v135, v190, v189, v139
	s_waitcnt lgkmcnt(4)
	ds_read2_b64 v[186:189], v238 offset0:16 offset1:17
	ds_read_b64 v[190:191], v238 offset:144
	v_cndmask_b32_e64 v192, v193, v192, s[4:5]
	v_cndmask_b32_e64 v193, v194, v193, s[4:5]
	v_cndmask_b32_e64 v194, v195, v194, s[4:5]
	v_cndmask_b32_e64 v195, v196, v195, s[4:5]
	v_cndmask_b32_e64 v196, v197, v196, s[4:5]
	v_alignbit_b32 v128, v193, v192, v139
	v_alignbit_b32 v129, v194, v193, v139
	v_alignbit_b32 v130, v195, v194, v139
	v_alignbit_b32 v131, v196, v195, v139
	s_waitcnt lgkmcnt(4)
	ds_read2_b64 v[192:195], v238 offset0:20 offset1:21
	ds_read_b64 v[196:197], v238 offset:176
	v_cndmask_b32_e64 v198, v199, v198, s[4:5]
	v_cndmask_b32_e64 v199, v200, v199, s[4:5]
	v_cndmask_b32_e64 v200, v201, v200, s[4:5]
	v_cndmask_b32_e64 v201, v202, v201, s[4:5]
	v_cndmask_b32_e64 v202, v203, v202, s[4:5]
	v_alignbit_b32 v124, v199, v198, v139
	v_alignbit_b32 v125, v200, v199, v139
	v_alignbit_b32 v126, v201, v200, v139
	v_alignbit_b32 v127, v202, v201, v139
	s_waitcnt lgkmcnt(4)
	ds_read2_b64 v[198:201], v238 offset0:24 offset1:25
	ds_read_b64 v[202:203], v238 offset:208
	v_cndmask_b32_e64 v204, v205, v204, s[4:5]
	v_cndmask_b32_e64 v205, v206, v205, s[4:5]
	v_cndmask_b32_e64 v206, v207, v206, s[4:5]
	v_cndmask_b32_e64 v207, v208, v207, s[4:5]
	v_cndmask_b32_e64 v208, v209, v208, s[4:5]
	v_alignbit_b32 v120, v205, v204, v139
	v_alignbit_b32 v121, v206, v205, v139
	v_alignbit_b32 v122, v207, v206, v139
	v_alignbit_b32 v123, v208, v207, v139
	s_waitcnt lgkmcnt(4)
	ds_read2_b64 v[204:207], v238 offset0:28 offset1:29
	ds_read_b64 v[208:209], v238 offset:240
	v_cndmask_b32_e64 v186, v187, v186, s[4:5]
	v_cndmask_b32_e64 v187, v188, v187, s[4:5]
	v_cndmask_b32_e64 v188, v189, v188, s[4:5]
	v_cndmask_b32_e64 v189, v190, v189, s[4:5]
	v_cndmask_b32_e64 v190, v191, v190, s[4:5]
	v_alignbit_b32 v116, v187, v186, v139
	v_alignbit_b32 v117, v188, v187, v139
	v_alignbit_b32 v118, v189, v188, v139
	v_alignbit_b32 v119, v190, v189, v139
	s_waitcnt lgkmcnt(4)
	v_cndmask_b32_e64 v192, v193, v192, s[4:5]
	v_cndmask_b32_e64 v193, v194, v193, s[4:5]
	v_cndmask_b32_e64 v194, v195, v194, s[4:5]
	v_cndmask_b32_e64 v195, v196, v195, s[4:5]
	v_cndmask_b32_e64 v196, v197, v196, s[4:5]
	v_alignbit_b32 v112, v193, v192, v139
	v_alignbit_b32 v113, v194, v193, v139
	v_alignbit_b32 v114, v195, v194, v139
	v_alignbit_b32 v115, v196, v195, v139
	s_waitcnt lgkmcnt(2)
	v_cndmask_b32_e64 v198, v199, v198, s[4:5]
	v_cndmask_b32_e64 v199, v200, v199, s[4:5]
	v_cndmask_b32_e64 v200, v201, v200, s[4:5]
	v_cndmask_b32_e64 v201, v202, v201, s[4:5]
	v_cndmask_b32_e64 v202, v203, v202, s[4:5]
	v_alignbit_b32 v92, v199, v198, v139
	v_alignbit_b32 v93, v200, v199, v139
	v_alignbit_b32 v94, v201, v200, v139
	v_alignbit_b32 v95, v202, v201, v139
	s_waitcnt lgkmcnt(0)
	v_cndmask_b32_e64 v204, v205, v204, s[4:5]
	v_cndmask_b32_e64 v205, v206, v205, s[4:5]
	v_cndmask_b32_e64 v206, v207, v206, s[4:5]
	v_cndmask_b32_e64 v207, v208, v207, s[4:5]
	v_cndmask_b32_e64 v208, v209, v208, s[4:5]
	v_alignbit_b32 v88, v205, v204, v139
	v_alignbit_b32 v89, v206, v205, v139
	v_alignbit_b32 v90, v207, v206, v139
	v_alignbit_b32 v91, v208, v207, v139
	s_barrier
	s_setprio 1
	s_waitcnt lgkmcnt(7)
	v_mfma_f32_32x32x16_bf16 v[48:63], v[92:95], v[100:103], v[48:63]
	v_mfma_f32_32x32x16_bf16 v[32:47], v[116:119], v[100:103], v[32:47]
	v_mfma_f32_32x32x16_bf16 v[16:31], v[124:127], v[100:103], v[16:31]
	v_mfma_f32_32x32x16_bf16 v[0:15], v[132:135], v[100:103], v[0:15]
	s_waitcnt lgkmcnt(6)
	v_mfma_f32_32x32x16_bf16 v[48:63], v[88:91], v[104:107], v[48:63]
	v_mfma_f32_32x32x16_bf16 v[32:47], v[112:115], v[104:107], v[32:47]
	v_mfma_f32_32x32x16_bf16 v[16:31], v[120:123], v[104:107], v[16:31]
	v_mfma_f32_32x32x16_bf16 v[0:15], v[128:131], v[104:107], v[0:15]
	s_waitcnt lgkmcnt(5)
	v_mfma_f32_32x32x16_bf16 v[48:63], v[64:67], v[148:151], v[48:63]
	v_mfma_f32_32x32x16_bf16 v[32:47], v[92:95], v[148:151], v[32:47]
	v_mfma_f32_32x32x16_bf16 v[16:31], v[116:119], v[148:151], v[16:31]
	v_mfma_f32_32x32x16_bf16 v[0:15], v[124:127], v[148:151], v[0:15]
	s_waitcnt lgkmcnt(4)
	v_mfma_f32_32x32x16_bf16 v[48:63], v[68:71], v[152:155], v[48:63]
	v_mfma_f32_32x32x16_bf16 v[32:47], v[88:91], v[152:155], v[32:47]
	v_mfma_f32_32x32x16_bf16 v[16:31], v[112:115], v[152:155], v[16:31]
	v_mfma_f32_32x32x16_bf16 v[0:15], v[120:123], v[152:155], v[0:15]
	s_waitcnt lgkmcnt(3)
	v_mfma_f32_32x32x16_bf16 v[48:63], v[72:75], v[156:159], v[48:63]
	v_mfma_f32_32x32x16_bf16 v[32:47], v[64:67], v[156:159], v[32:47]
	v_mfma_f32_32x32x16_bf16 v[16:31], v[92:95], v[156:159], v[16:31]
	v_mfma_f32_32x32x16_bf16 v[0:15], v[116:119], v[156:159], v[0:15]
	s_waitcnt lgkmcnt(2)
	v_mfma_f32_32x32x16_bf16 v[48:63], v[76:79], v[174:177], v[48:63]
	v_mfma_f32_32x32x16_bf16 v[32:47], v[68:71], v[174:177], v[32:47]
	v_mfma_f32_32x32x16_bf16 v[16:31], v[88:91], v[174:177], v[16:31]
	v_mfma_f32_32x32x16_bf16 v[0:15], v[112:115], v[174:177], v[0:15]
	s_waitcnt lgkmcnt(1)
	v_mfma_f32_32x32x16_bf16 v[48:63], v[80:83], v[178:181], v[48:63]
	v_mfma_f32_32x32x16_bf16 v[32:47], v[72:75], v[178:181], v[32:47]
	v_mfma_f32_32x32x16_bf16 v[16:31], v[64:67], v[178:181], v[16:31]
	v_mfma_f32_32x32x16_bf16 v[0:15], v[92:95], v[178:181], v[0:15]
	s_waitcnt lgkmcnt(0)
	v_mfma_f32_32x32x16_bf16 v[48:63], v[84:87], v[182:185], v[48:63]
	v_mfma_f32_32x32x16_bf16 v[32:47], v[76:79], v[182:185], v[32:47]
	v_mfma_f32_32x32x16_bf16 v[16:31], v[68:71], v[182:185], v[16:31]
	v_mfma_f32_32x32x16_bf16 v[0:15], v[88:91], v[182:185], v[0:15]
	s_setprio 0
	s_barrier
	s_add_i32 s8, s8, 2
	s_cmp_le_i32 s8, s2
	s_cbranch_scc0 .LBB0_523
	v_add_u32_e32 v73, -2, v143
	v_add_u32_e32 v74, 0xfffffde0, v110
	v_cmp_gt_u32_e32 vcc, s96, v73
	v_cndmask_b32_e64 v73, 0, 32, vcc
	v_cndmask_b32_e32 v74, v141, v74, vcc
	v_add_u32_e32 v80, v74, v73
	v_lshl_add_u32 v84, v73, 1, v74
	v_mad_u32_u24 v110, v73, 3, v74
	ds_read_b128 v[76:79], v74
	ds_read_b128 v[80:83], v80
	ds_read_b128 v[84:87], v84
	ds_read_b128 v[148:151], v110
	v_lshl_add_u32 v110, v73, 2, v74
	v_mad_u32_u24 v111, v73, 5, v74
	ds_read_b128 v[152:155], v110
	ds_read_b128 v[156:159], v111
	v_mad_u32_u24 v110, v73, 6, v74
	v_mad_u32_u24 v73, v73, 7, v74
	ds_read_b128 v[174:177], v110
	ds_read_b128 v[178:181], v73
	v_add_u32_e32 v238, 0x10940, v146
	ds_read2_b64 v[186:189], v238 offset0:0 offset1:1
	ds_read_b64 v[190:191], v238 offset:16
	ds_read2_b64 v[192:195], v238 offset0:4 offset1:5
	ds_read_b64 v[196:197], v238 offset:48
	ds_read2_b64 v[198:201], v238 offset0:8 offset1:9
	ds_read_b64 v[202:203], v238 offset:80
	s_waitcnt lgkmcnt(4)
	ds_read2_b64 v[204:207], v238 offset0:12 offset1:13
	ds_read_b64 v[208:209], v238 offset:112
	v_cndmask_b32_e64 v186, v187, v186, s[4:5]
	v_cndmask_b32_e64 v187, v188, v187, s[4:5]
	v_cndmask_b32_e64 v188, v189, v188, s[4:5]
	v_cndmask_b32_e64 v189, v190, v189, s[4:5]
	v_cndmask_b32_e64 v190, v191, v190, s[4:5]
	v_alignbit_b32 v108, v187, v186, v139
	v_alignbit_b32 v109, v188, v187, v139
	v_alignbit_b32 v110, v189, v188, v139
	v_alignbit_b32 v111, v190, v189, v139
	s_waitcnt lgkmcnt(4)
	ds_read2_b64 v[186:189], v238 offset0:16 offset1:17
	ds_read_b64 v[190:191], v238 offset:144
	v_cndmask_b32_e64 v192, v193, v192, s[4:5]
	v_cndmask_b32_e64 v193, v194, v193, s[4:5]
	v_cndmask_b32_e64 v194, v195, v194, s[4:5]
	v_cndmask_b32_e64 v195, v196, v195, s[4:5]
	v_cndmask_b32_e64 v196, v197, v196, s[4:5]
	v_alignbit_b32 v96, v193, v192, v139
	v_alignbit_b32 v97, v194, v193, v139
	v_alignbit_b32 v98, v195, v194, v139
	v_alignbit_b32 v99, v196, v195, v139
	s_waitcnt lgkmcnt(4)
	ds_read2_b64 v[192:195], v238 offset0:20 offset1:21
	ds_read_b64 v[196:197], v238 offset:176
	v_cndmask_b32_e64 v198, v199, v198, s[4:5]
	v_cndmask_b32_e64 v199, v200, v199, s[4:5]
	v_cndmask_b32_e64 v200, v201, v200, s[4:5]
	v_cndmask_b32_e64 v201, v202, v201, s[4:5]
	v_cndmask_b32_e64 v202, v203, v202, s[4:5]
	v_alignbit_b32 v104, v199, v198, v139
	v_alignbit_b32 v105, v200, v199, v139
	v_alignbit_b32 v106, v201, v200, v139
	v_alignbit_b32 v107, v202, v201, v139
	s_waitcnt lgkmcnt(4)
	ds_read2_b64 v[198:201], v238 offset0:24 offset1:25
	ds_read_b64 v[202:203], v238 offset:208
	v_cndmask_b32_e64 v204, v205, v204, s[4:5]
	v_cndmask_b32_e64 v205, v206, v205, s[4:5]
	v_cndmask_b32_e64 v206, v207, v206, s[4:5]
	v_cndmask_b32_e64 v207, v208, v207, s[4:5]
	v_cndmask_b32_e64 v208, v209, v208, s[4:5]
	v_alignbit_b32 v92, v205, v204, v139
	v_alignbit_b32 v93, v206, v205, v139
	v_alignbit_b32 v94, v207, v206, v139
	v_alignbit_b32 v95, v208, v207, v139
	s_waitcnt lgkmcnt(4)
	ds_read2_b64 v[204:207], v238 offset0:28 offset1:29
	ds_read_b64 v[208:209], v238 offset:240
	v_cndmask_b32_e64 v186, v187, v186, s[4:5]
	v_cndmask_b32_e64 v187, v188, v187, s[4:5]
	v_cndmask_b32_e64 v188, v189, v188, s[4:5]
	v_cndmask_b32_e64 v189, v190, v189, s[4:5]
	v_cndmask_b32_e64 v190, v191, v190, s[4:5]
	v_alignbit_b32 v100, v187, v186, v139
	v_alignbit_b32 v101, v188, v187, v139
	v_alignbit_b32 v102, v189, v188, v139
	v_alignbit_b32 v103, v190, v189, v139
	s_waitcnt lgkmcnt(4)
	v_cndmask_b32_e64 v192, v193, v192, s[4:5]
	v_cndmask_b32_e64 v193, v194, v193, s[4:5]
	v_cndmask_b32_e64 v194, v195, v194, s[4:5]
	v_cndmask_b32_e64 v195, v196, v195, s[4:5]
	v_cndmask_b32_e64 v196, v197, v196, s[4:5]
	v_alignbit_b32 v88, v193, v192, v139
	v_alignbit_b32 v89, v194, v193, v139
	v_alignbit_b32 v90, v195, v194, v139
	v_alignbit_b32 v91, v196, v195, v139
	s_waitcnt lgkmcnt(2)
	v_cndmask_b32_e64 v198, v199, v198, s[4:5]
	v_cndmask_b32_e64 v199, v200, v199, s[4:5]
	v_cndmask_b32_e64 v200, v201, v200, s[4:5]
	v_cndmask_b32_e64 v201, v202, v201, s[4:5]
	v_cndmask_b32_e64 v202, v203, v202, s[4:5]
	v_alignbit_b32 v68, v199, v198, v139
	v_alignbit_b32 v69, v200, v199, v139
	v_alignbit_b32 v70, v201, v200, v139
	v_alignbit_b32 v71, v202, v201, v139
	s_waitcnt lgkmcnt(0)
	v_cndmask_b32_e64 v204, v205, v204, s[4:5]
	v_cndmask_b32_e64 v205, v206, v205, s[4:5]
	v_cndmask_b32_e64 v206, v207, v206, s[4:5]
	v_cndmask_b32_e64 v207, v208, v207, s[4:5]
	v_cndmask_b32_e64 v208, v209, v208, s[4:5]
	v_alignbit_b32 v64, v205, v204, v139
	v_alignbit_b32 v65, v206, v205, v139
	v_alignbit_b32 v66, v207, v206, v139
	v_alignbit_b32 v67, v208, v207, v139
	s_barrier
	s_setprio 1
	s_waitcnt lgkmcnt(7)
	v_mfma_f32_32x32x16_bf16 v[48:63], v[68:71], v[76:79], v[48:63]
	v_mfma_f32_32x32x16_bf16 v[32:47], v[100:103], v[76:79], v[32:47]
	v_mfma_f32_32x32x16_bf16 v[16:31], v[104:107], v[76:79], v[16:31]
	v_mfma_f32_32x32x16_bf16 v[0:15], v[108:111], v[76:79], v[0:15]
	s_waitcnt lgkmcnt(6)
	v_mfma_f32_32x32x16_bf16 v[48:63], v[64:67], v[80:83], v[48:63]
	v_mfma_f32_32x32x16_bf16 v[32:47], v[88:91], v[80:83], v[32:47]
	v_mfma_f32_32x32x16_bf16 v[16:31], v[92:95], v[80:83], v[16:31]
	v_mfma_f32_32x32x16_bf16 v[0:15], v[96:99], v[80:83], v[0:15]
	s_waitcnt lgkmcnt(5)
	v_mfma_f32_32x32x16_bf16 v[48:63], v[132:135], v[84:87], v[48:63]
	v_mfma_f32_32x32x16_bf16 v[32:47], v[68:71], v[84:87], v[32:47]
	v_mfma_f32_32x32x16_bf16 v[16:31], v[100:103], v[84:87], v[16:31]
	v_mfma_f32_32x32x16_bf16 v[0:15], v[104:107], v[84:87], v[0:15]
	s_waitcnt lgkmcnt(4)
	v_mfma_f32_32x32x16_bf16 v[48:63], v[128:131], v[148:151], v[48:63]
	v_mfma_f32_32x32x16_bf16 v[32:47], v[64:67], v[148:151], v[32:47]
	v_mfma_f32_32x32x16_bf16 v[16:31], v[88:91], v[148:151], v[16:31]
	v_mfma_f32_32x32x16_bf16 v[0:15], v[92:95], v[148:151], v[0:15]
	s_waitcnt lgkmcnt(3)
	v_mfma_f32_32x32x16_bf16 v[48:63], v[124:127], v[152:155], v[48:63]
	v_mfma_f32_32x32x16_bf16 v[32:47], v[132:135], v[152:155], v[32:47]
	v_mfma_f32_32x32x16_bf16 v[16:31], v[68:71], v[152:155], v[16:31]
	v_mfma_f32_32x32x16_bf16 v[0:15], v[100:103], v[152:155], v[0:15]
	s_waitcnt lgkmcnt(2)
	v_mfma_f32_32x32x16_bf16 v[48:63], v[120:123], v[156:159], v[48:63]
	v_mfma_f32_32x32x16_bf16 v[32:47], v[128:131], v[156:159], v[32:47]
	v_mfma_f32_32x32x16_bf16 v[16:31], v[64:67], v[156:159], v[16:31]
	v_mfma_f32_32x32x16_bf16 v[0:15], v[88:91], v[156:159], v[0:15]
	s_waitcnt lgkmcnt(1)
	v_mfma_f32_32x32x16_bf16 v[48:63], v[116:119], v[174:177], v[48:63]
	v_mfma_f32_32x32x16_bf16 v[32:47], v[124:127], v[174:177], v[32:47]
	v_mfma_f32_32x32x16_bf16 v[16:31], v[132:135], v[174:177], v[16:31]
	v_mfma_f32_32x32x16_bf16 v[0:15], v[68:71], v[174:177], v[0:15]
	s_waitcnt lgkmcnt(0)
	v_mfma_f32_32x32x16_bf16 v[48:63], v[112:115], v[178:181], v[48:63]
	v_mfma_f32_32x32x16_bf16 v[32:47], v[120:123], v[178:181], v[32:47]
	v_mfma_f32_32x32x16_bf16 v[16:31], v[128:131], v[178:181], v[16:31]
	v_mfma_f32_32x32x16_bf16 v[0:15], v[64:67], v[178:181], v[0:15]
	s_setprio 0
	s_barrier
	v_add_u32_e32 v238, 0x10840, v146
	ds_read2_b64 v[186:189], v238 offset0:0 offset1:1
	ds_read_b64 v[190:191], v238 offset:16
	ds_read2_b64 v[192:195], v238 offset0:4 offset1:5
	ds_read_b64 v[196:197], v238 offset:48
	ds_read2_b64 v[198:201], v238 offset0:8 offset1:9
	ds_read_b64 v[202:203], v238 offset:80
	s_waitcnt lgkmcnt(4)
	ds_read2_b64 v[204:207], v238 offset0:12 offset1:13
	ds_read_b64 v[208:209], v238 offset:112
	v_cndmask_b32_e64 v186, v187, v186, s[4:5]
	v_cndmask_b32_e64 v187, v188, v187, s[4:5]
	v_cndmask_b32_e64 v188, v189, v188, s[4:5]
	v_cndmask_b32_e64 v189, v190, v189, s[4:5]
	v_cndmask_b32_e64 v190, v191, v190, s[4:5]
	v_alignbit_b32 v64, v187, v186, v139
	v_alignbit_b32 v65, v188, v187, v139
	v_alignbit_b32 v66, v189, v188, v139
	v_alignbit_b32 v67, v190, v189, v139
	s_waitcnt lgkmcnt(4)
	ds_read2_b64 v[186:189], v238 offset0:16 offset1:17
	ds_read_b64 v[190:191], v238 offset:144
	v_cndmask_b32_e64 v192, v193, v192, s[4:5]
	v_cndmask_b32_e64 v193, v194, v193, s[4:5]
	v_cndmask_b32_e64 v194, v195, v194, s[4:5]
	v_cndmask_b32_e64 v195, v196, v195, s[4:5]
	v_cndmask_b32_e64 v196, v197, v196, s[4:5]
	v_alignbit_b32 v68, v193, v192, v139
	v_alignbit_b32 v69, v194, v193, v139
	v_alignbit_b32 v70, v195, v194, v139
	v_alignbit_b32 v71, v196, v195, v139
	s_waitcnt lgkmcnt(4)
	ds_read2_b64 v[192:195], v238 offset0:20 offset1:21
	ds_read_b64 v[196:197], v238 offset:176
	v_cndmask_b32_e64 v198, v199, v198, s[4:5]
	v_cndmask_b32_e64 v199, v200, v199, s[4:5]
	v_cndmask_b32_e64 v200, v201, v200, s[4:5]
	v_cndmask_b32_e64 v201, v202, v201, s[4:5]
	v_cndmask_b32_e64 v202, v203, v202, s[4:5]
	v_alignbit_b32 v72, v199, v198, v139
	v_alignbit_b32 v73, v200, v199, v139
	v_alignbit_b32 v74, v201, v200, v139
	v_alignbit_b32 v75, v202, v201, v139
	s_waitcnt lgkmcnt(4)
	ds_read2_b64 v[198:201], v238 offset0:24 offset1:25
	ds_read_b64 v[202:203], v238 offset:208
	v_cndmask_b32_e64 v204, v205, v204, s[4:5]
	v_cndmask_b32_e64 v205, v206, v205, s[4:5]
	v_cndmask_b32_e64 v206, v207, v206, s[4:5]
	v_cndmask_b32_e64 v207, v208, v207, s[4:5]
	v_cndmask_b32_e64 v208, v209, v208, s[4:5]
	v_alignbit_b32 v76, v205, v204, v139
	v_alignbit_b32 v77, v206, v205, v139
	v_alignbit_b32 v78, v207, v206, v139
	v_alignbit_b32 v79, v208, v207, v139
	s_waitcnt lgkmcnt(4)
	ds_read2_b64 v[204:207], v238 offset0:28 offset1:29
	ds_read_b64 v[208:209], v238 offset:240
	v_cndmask_b32_e64 v186, v187, v186, s[4:5]
	v_cndmask_b32_e64 v187, v188, v187, s[4:5]
	v_cndmask_b32_e64 v188, v189, v188, s[4:5]
	v_cndmask_b32_e64 v189, v190, v189, s[4:5]
	v_cndmask_b32_e64 v190, v191, v190, s[4:5]
	v_alignbit_b32 v80, v187, v186, v139
	v_alignbit_b32 v81, v188, v187, v139
	v_alignbit_b32 v82, v189, v188, v139
	v_alignbit_b32 v83, v190, v189, v139
	s_waitcnt lgkmcnt(4)
	v_cndmask_b32_e64 v192, v193, v192, s[4:5]
	v_cndmask_b32_e64 v193, v194, v193, s[4:5]
	v_cndmask_b32_e64 v194, v195, v194, s[4:5]
	v_cndmask_b32_e64 v195, v196, v195, s[4:5]
	v_cndmask_b32_e64 v196, v197, v196, s[4:5]
	v_alignbit_b32 v84, v193, v192, v139
	v_alignbit_b32 v85, v194, v193, v139
	v_alignbit_b32 v86, v195, v194, v139
	v_alignbit_b32 v87, v196, v195, v139
	s_waitcnt lgkmcnt(2)
	v_cndmask_b32_e64 v198, v199, v198, s[4:5]
	v_cndmask_b32_e64 v199, v200, v199, s[4:5]
	v_cndmask_b32_e64 v200, v201, v200, s[4:5]
	v_cndmask_b32_e64 v201, v202, v201, s[4:5]
	v_cndmask_b32_e64 v202, v203, v202, s[4:5]
	v_alignbit_b32 v112, v199, v198, v139
	v_alignbit_b32 v113, v200, v199, v139
	v_alignbit_b32 v114, v201, v200, v139
	v_alignbit_b32 v115, v202, v201, v139
	s_waitcnt lgkmcnt(0)
	v_cndmask_b32_e64 v204, v205, v204, s[4:5]
	v_cndmask_b32_e64 v205, v206, v205, s[4:5]
	v_cndmask_b32_e64 v206, v207, v206, s[4:5]
	v_cndmask_b32_e64 v207, v208, v207, s[4:5]
	v_cndmask_b32_e64 v208, v209, v208, s[4:5]
	v_alignbit_b32 v116, v205, v204, v139
	v_alignbit_b32 v117, v206, v205, v139
	v_alignbit_b32 v118, v207, v206, v139
	v_alignbit_b32 v119, v208, v207, v139
	s_add_i32 s9, s8, 1
	s_cmp_gt_i32 s9, s2
	v_add_u32_e32 v142, 0xfffffcd0, v142
	v_add_u32_e32 v143, -3, v143
	v_add_u32_e32 v144, 0xfffffcd0, v144
	v_add_u32_e32 v145, 0xfffffd00, v145
	s_cselect_b64 s[6:7], -1, 0
	s_and_b64 vcc, exec, s[6:7]
	s_mov_b32 s8, s9
	s_cbranch_vccz .LBB0_524
.LBB0_527:
	s_cmpk_lt_u32 s0, 0x100
	s_cbranch_scc1 .Lsb_b
	s_barrier
